# ret_out closing rescale: 16 loads in flight instead of 16 serial round trips; weight-conversion items: the 32 gain values requested up front instead of pairwise behind vmcnt(0)
# speedup vs baseline: 1.0159x; 1.0159x over previous
; #define LAS __attribute__((address_space(3)))
; __device__ __forceinline__ void transpose_item(const float* W, int N, bf16* WT, int K, int k0, int n0, int drow0, const float* gk, LAS float* scr, int lane) {
;     float wv[32];
; #pragma unroll
;     for (int i = 0; i < 32; ++i) wv[i] = W[(size_t)(k0 + 2 * i + (lane >> 5)) * N + n0 + (lane & 31)];
; __device__ __forceinline__ void p0_weight_item(const Args& a, int l, int r, LAS float* scr, int lane) {
;     ...
;     if (r < IT_OUT) {
;         const int kb = r / 32, nb = r % 32, k0 = 64 * kb;
;         const float* gk = (k0 < 256) ? a.in[17] + (size_t)l * 256 + k0 : (k0 < 768 ? a.in[18] + (size_t)l * 512 + (k0 - 256) : a.in[26] + (size_t)l * 256 + (k0 - 768));
;         transpose_item(a.in[27] + (size_t)l * DM * DM, DM, (bf16*)(wl + WL_WOUT), DM, k0, 32 * nb, 32 * nb, gk, scr, lane); return; }
.LBB0_34:
	v_readlane_b32 s52, v250, 59
	s_lshl_b64 s[4:5], s[26:27], 22
	v_readlane_b32 s58, v251, 1
	v_readlane_b32 s59, v251, 2
	s_add_u32 s4, s58, s4
	s_addc_u32 s5, s59, s5
	s_lshl_b32 s27, s26, 9
	s_sub_i32 s27, s43, s27
	s_add_i32 s27, s27, 0xfffbe000
	s_and_b32 s27, s27, 0x3e0
	s_lshl_b32 s30, s27, 2
	v_or_b32_e32 v12, s16, v4
	s_add_u32 s4, s4, s30
	s_addc_u32 s5, s5, 0
	v_or_b32_e32 v26, 10, v12
	v_mov_b32_e32 v27, v7
	v_lshl_add_u64 v[14:15], s[4:5], 0, v[6:7]
	v_lshlrev_b64 v[26:27], 12, v[26:27]
	v_lshl_add_u64 v[28:29], v[14:15], 0, v[26:27]
	v_or_b32_e32 v26, 12, v12
	v_mov_b32_e32 v27, v7
	v_mov_b32_e32 v13, v7
	v_or_b32_e32 v22, 6, v12
	v_mov_b32_e32 v23, v7
	v_or_b32_e32 v24, 8, v12
	v_mov_b32_e32 v25, v7
	v_lshlrev_b64 v[26:27], 12, v[26:27]
	v_lshlrev_b64 v[16:17], 12, v[12:13]
	v_or_b32_e32 v18, 2, v12
	v_mov_b32_e32 v19, v7
	v_or_b32_e32 v20, 4, v12
	v_mov_b32_e32 v21, v7
	v_lshlrev_b64 v[22:23], 12, v[22:23]
	v_lshlrev_b64 v[24:25], 12, v[24:25]
	v_lshl_add_u64 v[56:57], v[14:15], 0, v[26:27]
	v_or_b32_e32 v26, 14, v12
	v_mov_b32_e32 v27, v7
	v_lshl_add_u64 v[16:17], v[14:15], 0, v[16:17]
	v_lshlrev_b64 v[18:19], 12, v[18:19]
	v_lshlrev_b64 v[20:21], 12, v[20:21]
	v_lshl_add_u64 v[22:23], v[14:15], 0, v[22:23]
	v_lshl_add_u64 v[24:25], v[14:15], 0, v[24:25]
	v_lshlrev_b64 v[26:27], 12, v[26:27]
	v_lshl_add_u64 v[18:19], v[14:15], 0, v[18:19]
	v_lshl_add_u64 v[20:21], v[14:15], 0, v[20:21]
	v_lshl_add_u64 v[58:59], v[14:15], 0, v[26:27]
	global_load_dword v68, v[16:17], off
	global_load_dword v67, v[18:19], off
	global_load_dword v26, v[20:21], off
	global_load_dword v27, v[22:23], off
	global_load_dword v65, v[24:25], off
	global_load_dword v66, v[28:29], off
	s_nop 0
	global_load_dword v24, v[56:57], off
	global_load_dword v25, v[58:59], off
	v_or_b32_e32 v22, 22, v12
	v_mov_b32_e32 v23, v7
	v_lshlrev_b64 v[22:23], 12, v[22:23]
	v_lshl_add_u64 v[28:29], v[14:15], 0, v[22:23]
	v_or_b32_e32 v22, 24, v12
	v_mov_b32_e32 v23, v7
	v_lshlrev_b64 v[22:23], 12, v[22:23]
	v_lshl_add_u64 v[56:57], v[14:15], 0, v[22:23]
	v_or_b32_e32 v22, 26, v12
	v_mov_b32_e32 v23, v7
	v_lshlrev_b64 v[22:23], 12, v[22:23]
	v_lshl_add_u64 v[58:59], v[14:15], 0, v[22:23]
	v_or_b32_e32 v22, 28, v12
	v_mov_b32_e32 v23, v7
	v_or_b32_e32 v16, 16, v12
	v_mov_b32_e32 v17, v7
	v_or_b32_e32 v20, 20, v12
	v_mov_b32_e32 v21, v7
	v_lshlrev_b64 v[22:23], 12, v[22:23]
	v_lshlrev_b64 v[16:17], 12, v[16:17]
	v_or_b32_e32 v18, 18, v12
	v_mov_b32_e32 v19, v7
	v_lshlrev_b64 v[20:21], 12, v[20:21]
	v_lshl_add_u64 v[70:71], v[14:15], 0, v[22:23]
	v_or_b32_e32 v22, 30, v12
	v_mov_b32_e32 v23, v7
	v_lshl_add_u64 v[16:17], v[14:15], 0, v[16:17]
	v_lshlrev_b64 v[18:19], 12, v[18:19]
	v_lshl_add_u64 v[20:21], v[14:15], 0, v[20:21]
	v_lshlrev_b64 v[22:23], 12, v[22:23]
	v_lshl_add_u64 v[18:19], v[14:15], 0, v[18:19]
	v_lshl_add_u64 v[72:73], v[14:15], 0, v[22:23]
	global_load_dword v63, v[16:17], off
	global_load_dword v64, v[18:19], off
	global_load_dword v22, v[20:21], off
	global_load_dword v23, v[28:29], off
	global_load_dword v61, v[56:57], off
	global_load_dword v62, v[58:59], off
	s_nop 0
	global_load_dword v20, v[70:71], off
	global_load_dword v21, v[72:73], off
	v_or_b32_e32 v58, 40, v12
	v_mov_b32_e32 v59, v7
	v_lshlrev_b64 v[58:59], 12, v[58:59]
	v_lshl_add_u64 v[70:71], v[14:15], 0, v[58:59]
	v_or_b32_e32 v58, 42, v12
	v_mov_b32_e32 v59, v7
	v_lshlrev_b64 v[58:59], 12, v[58:59]
	v_lshl_add_u64 v[72:73], v[14:15], 0, v[58:59]
	v_or_b32_e32 v58, 44, v12
	v_mov_b32_e32 v59, v7
	v_or_b32_e32 v16, 32, v12
	v_mov_b32_e32 v17, v7
	v_or_b32_e32 v18, 34, v12
	v_mov_b32_e32 v19, v7
	v_or_b32_e32 v28, 36, v12
	v_mov_b32_e32 v29, v7
	v_or_b32_e32 v56, 38, v12
	v_mov_b32_e32 v57, v7
	v_lshlrev_b64 v[58:59], 12, v[58:59]
	v_lshlrev_b64 v[16:17], 12, v[16:17]
	v_lshlrev_b64 v[18:19], 12, v[18:19]
	v_lshlrev_b64 v[28:29], 12, v[28:29]
	v_lshlrev_b64 v[56:57], 12, v[56:57]
	v_lshl_add_u64 v[74:75], v[14:15], 0, v[58:59]
	v_or_b32_e32 v58, 46, v12
	v_mov_b32_e32 v59, v7
	v_lshl_add_u64 v[16:17], v[14:15], 0, v[16:17]
	v_lshl_add_u64 v[18:19], v[14:15], 0, v[18:19]
	v_lshl_add_u64 v[28:29], v[14:15], 0, v[28:29]
	v_lshl_add_u64 v[56:57], v[14:15], 0, v[56:57]
	v_lshlrev_b64 v[58:59], 12, v[58:59]
	v_lshl_add_u64 v[76:77], v[14:15], 0, v[58:59]
	global_load_dword v59, v[16:17], off
	global_load_dword v60, v[18:19], off
	s_nop 0
	global_load_dword v18, v[28:29], off
	global_load_dword v19, v[56:57], off
	s_nop 0
	global_load_dword v57, v[70:71], off
	global_load_dword v58, v[72:73], off
	global_load_dword v16, v[74:75], off
	global_load_dword v17, v[76:77], off
	v_or_b32_e32 v28, 48, v12
	v_mov_b32_e32 v29, v7
	v_lshlrev_b64 v[28:29], 12, v[28:29]
	v_or_b32_e32 v70, 50, v12
	v_mov_b32_e32 v71, v7
	v_or_b32_e32 v72, 52, v12
	v_mov_b32_e32 v73, v7
	v_or_b32_e32 v74, 54, v12
	v_mov_b32_e32 v75, v7
	v_or_b32_e32 v76, 56, v12
	v_mov_b32_e32 v77, v7
	v_or_b32_e32 v78, 58, v12
	v_mov_b32_e32 v79, v7
	v_or_b32_e32 v80, 60, v12
	v_mov_b32_e32 v81, v7
	v_or_b32_e32 v12, 62, v12
	v_lshl_add_u64 v[28:29], v[14:15], 0, v[28:29]
	v_lshlrev_b64 v[70:71], 12, v[70:71]
	v_lshlrev_b64 v[72:73], 12, v[72:73]
	v_lshlrev_b64 v[74:75], 12, v[74:75]
	v_lshlrev_b64 v[76:77], 12, v[76:77]
	v_lshlrev_b64 v[78:79], 12, v[78:79]
	v_lshlrev_b64 v[80:81], 12, v[80:81]
	v_lshlrev_b64 v[12:13], 12, v[12:13]
	v_lshl_add_u64 v[70:71], v[14:15], 0, v[70:71]
	v_lshl_add_u64 v[72:73], v[14:15], 0, v[72:73]
	v_lshl_add_u64 v[74:75], v[14:15], 0, v[74:75]
	v_lshl_add_u64 v[76:77], v[14:15], 0, v[76:77]
	v_lshl_add_u64 v[78:79], v[14:15], 0, v[78:79]
	v_lshl_add_u64 v[80:81], v[14:15], 0, v[80:81]
	v_lshl_add_u64 v[82:83], v[14:15], 0, v[12:13]
	global_load_dword v55, v[28:29], off
	global_load_dword v56, v[70:71], off
	global_load_dword v14, v[72:73], off
	global_load_dword v15, v[74:75], off
	global_load_dword v9, v[76:77], off
	global_load_dword v11, v[78:79], off
	global_load_dword v12, v[80:81], off
	global_load_dword v13, v[82:83], off
	s_cmp_lg_u64 s[28:29], 0
	s_cselect_b64 s[30:31], -1, 0
	s_cmp_eq_u64 s[28:29], 0
	v_readlane_b32 s53, v250, 60
	v_readlane_b32 s54, v250, 61
	v_readlane_b32 s55, v250, 62
	v_readlane_b32 s56, v250, 63
	v_readlane_b32 s57, v251, 0
	v_readlane_b32 s60, v251, 3
	v_readlane_b32 s61, v251, 4
	v_readlane_b32 s62, v251, 5
	v_readlane_b32 s63, v251, 6
	v_readlane_b32 s64, v251, 7
	v_readlane_b32 s65, v251, 8
	v_readlane_b32 s66, v251, 9
	v_readlane_b32 s67, v251, 10
	s_cbranch_scc1 .LBB0_170
; __device__ __forceinline__ void lds_wait() { asm volatile("s_waitcnt lgkmcnt(0)" ::: "memory"); }
; __device__ __forceinline__ void transpose_item(const float* W, int N, bf16* WT, int K, int k0, int n0, int drow0, const float* gk, LAS float* scr, int lane) {
;     ...
;     for (int i = 0; i < 32; ++i) wv[i] = W[(size_t)(k0 + 2 * i + (lane >> 5)) * N + n0 + (lane & 31)];
; #pragma unroll
;     for (int i = 0; i < 32; ++i) { const int kk = 2 * i + (lane >> 5); float v = wv[i]; if (gk) v *= gk[kk]; scr[kk * 33 + (lane & 31)] = v; }
;     lds_wait();
	v_lshlrev_b32_e32 v29, 2, v4
	s_waitcnt vmcnt(32)
	global_load_dword v204, v29, s[28:29]
	global_load_dword v205, v29, s[28:29] offset:8
	global_load_dword v206, v29, s[28:29] offset:16
	global_load_dword v207, v29, s[28:29] offset:24
	global_load_dword v208, v29, s[28:29] offset:32
	global_load_dword v209, v29, s[28:29] offset:40
	global_load_dword v210, v29, s[28:29] offset:48
	global_load_dword v211, v29, s[28:29] offset:56
	global_load_dword v212, v29, s[28:29] offset:64
	global_load_dword v213, v29, s[28:29] offset:72
	global_load_dword v214, v29, s[28:29] offset:80
	global_load_dword v215, v29, s[28:29] offset:88
	global_load_dword v216, v29, s[28:29] offset:96
	global_load_dword v217, v29, s[28:29] offset:104
	global_load_dword v218, v29, s[28:29] offset:112
	global_load_dword v219, v29, s[28:29] offset:120
	global_load_dword v220, v29, s[28:29] offset:128
	global_load_dword v221, v29, s[28:29] offset:136
	global_load_dword v222, v29, s[28:29] offset:144
	global_load_dword v223, v29, s[28:29] offset:152
	global_load_dword v224, v29, s[28:29] offset:160
	global_load_dword v225, v29, s[28:29] offset:168
	global_load_dword v226, v29, s[28:29] offset:176
	global_load_dword v227, v29, s[28:29] offset:184
	global_load_dword v228, v29, s[28:29] offset:192
	global_load_dword v229, v29, s[28:29] offset:200
	global_load_dword v230, v29, s[28:29] offset:208
	global_load_dword v231, v29, s[28:29] offset:216
	global_load_dword v232, v29, s[28:29] offset:224
	global_load_dword v233, v29, s[28:29] offset:232
	global_load_dword v234, v29, s[28:29] offset:240
	s_waitcnt vmcnt(62)
	global_load_dword v235, v29, s[28:29] offset:248
	s_waitcnt vmcnt(0)
	v_mov_b32_e32 v69, v204
	v_mov_b32_e32 v70, v205
	v_mov_b32_e32 v28, v206
	s_nop 0
	v_mov_b32_e32 v29, v207
	v_add_u32_e32 v71, v3, v35
	s_waitcnt vmcnt(3)
	v_mul_f32_e32 v69, v68, v69
	s_waitcnt vmcnt(2)
	v_mul_f32_e32 v70, v67, v70
	ds_write_b32 v5, v69
	ds_write_b32 v71, v70
	s_waitcnt vmcnt(0)
	v_pk_mul_f32 v[28:29], v[26:27], v[28:29]
	s_cbranch_execnz .LBB0_37

; __device__ __forceinline__ void transpose_item(const float* W, int N, bf16* WT, int K, int k0, int n0, int drow0, const float* gk, LAS float* scr, int lane) {
;     ...
; #pragma unroll
;     for (int i = 0; i < 32; ++i) { const int kk = 2 * i + (lane >> 5); float v = wv[i]; if (gk) v *= gk[kk]; scr[kk * 33 + (lane & 31)] = v; }
.LBB0_37:
	s_waitcnt vmcnt(28)
	v_cndmask_b32_e64 v27, 0, 1, s[30:31]
	v_add_u32_e32 v26, v3, v36
	v_cmp_ne_u32_e64 s[4:5], 1, v27
	s_andn2_b64 vcc, exec, s[30:31]
	ds_write2_b32 v26, v28, v29 offset1:66
	s_cbranch_vccnz .LBB0_171
	v_lshlrev_b32_e32 v27, 2, v4
	v_mov_b32_e32 v28, v208
	v_mov_b32_e32 v29, v209
	v_mov_b32_e32 v26, v210
	s_nop 0
	v_mov_b32_e32 v27, v211
	v_add_u32_e32 v67, v3, v37
	s_waitcnt vmcnt(3)
	v_mul_f32_e32 v28, v65, v28
	s_waitcnt vmcnt(2)
	v_mul_f32_e32 v29, v66, v29
	ds_write2_b32 v67, v28, v29 offset1:66
	s_waitcnt vmcnt(0)
	v_pk_mul_f32 v[26:27], v[24:25], v[26:27]
	s_cbranch_execnz .LBB0_40

; __device__ __forceinline__ void transpose_item(const float* W, int N, bf16* WT, int K, int k0, int n0, int drow0, const float* gk, LAS float* scr, int lane) {
;     ...
; #pragma unroll
;     for (int i = 0; i < 32; ++i) { const int kk = 2 * i + (lane >> 5); float v = wv[i]; if (gk) v *= gk[kk]; scr[kk * 33 + (lane & 31)] = v; }
.LBB0_40:
	s_waitcnt vmcnt(25)
	v_add_u32_e32 v24, v3, v38
	s_and_b64 vcc, exec, s[4:5]
	ds_write2_b32 v24, v26, v27 offset1:66
	s_cbranch_vccnz .LBB0_172
	s_waitcnt vmcnt(24)
	v_lshlrev_b32_e32 v25, 2, v4
	v_mov_b32_e32 v26, v212
	v_mov_b32_e32 v27, v213
	v_mov_b32_e32 v24, v214
	s_nop 0
	v_mov_b32_e32 v25, v215
	v_add_u32_e32 v28, v3, v39
	s_waitcnt vmcnt(3)
	v_mul_f32_e32 v26, v63, v26
	s_waitcnt vmcnt(2)
	v_mul_f32_e32 v27, v64, v27
	ds_write2_b32 v28, v26, v27 offset1:66
	s_waitcnt vmcnt(0)
	v_pk_mul_f32 v[24:25], v[22:23], v[24:25]
	s_cbranch_execnz .LBB0_43

; __device__ __forceinline__ void transpose_item(const float* W, int N, bf16* WT, int K, int k0, int n0, int drow0, const float* gk, LAS float* scr, int lane) {
;     ...
; #pragma unroll
;     for (int i = 0; i < 32; ++i) { const int kk = 2 * i + (lane >> 5); float v = wv[i]; if (gk) v *= gk[kk]; scr[kk * 33 + (lane & 31)] = v; }
.LBB0_43:
	s_waitcnt vmcnt(21)
	v_add_u32_e32 v22, v3, v40
	s_and_b64 vcc, exec, s[4:5]
	ds_write2_b32 v22, v24, v25 offset1:66
	s_cbranch_vccnz .LBB0_173
	s_waitcnt vmcnt(20)
	v_lshlrev_b32_e32 v23, 2, v4
	v_mov_b32_e32 v24, v216
	v_mov_b32_e32 v25, v217
	v_mov_b32_e32 v22, v218
	s_nop 0
	v_mov_b32_e32 v23, v219
	v_add_u32_e32 v26, v3, v41
	s_waitcnt vmcnt(3)
	v_mul_f32_e32 v24, v61, v24
	s_waitcnt vmcnt(2)
	v_mul_f32_e32 v25, v62, v25
	ds_write2_b32 v26, v24, v25 offset1:66
	s_waitcnt vmcnt(0)
	v_pk_mul_f32 v[22:23], v[20:21], v[22:23]
	s_cbranch_execnz .LBB0_46

; __device__ __forceinline__ void transpose_item(const float* W, int N, bf16* WT, int K, int k0, int n0, int drow0, const float* gk, LAS float* scr, int lane) {
;     ...
; #pragma unroll
;     for (int i = 0; i < 32; ++i) { const int kk = 2 * i + (lane >> 5); float v = wv[i]; if (gk) v *= gk[kk]; scr[kk * 33 + (lane & 31)] = v; }
.LBB0_46:
	s_waitcnt vmcnt(17)
	v_add_u32_e32 v20, v3, v42
	s_and_b64 vcc, exec, s[4:5]
	ds_write2_b32 v20, v22, v23 offset1:66
	s_cbranch_vccnz .LBB0_174
	s_waitcnt vmcnt(16)
	v_lshlrev_b32_e32 v21, 2, v4
	v_mov_b32_e32 v22, v220
	v_mov_b32_e32 v23, v221
	v_mov_b32_e32 v20, v222
	s_nop 0
	v_mov_b32_e32 v21, v223
	v_add_u32_e32 v24, v3, v43
	s_waitcnt vmcnt(3)
	v_mul_f32_e32 v22, v59, v22
	s_waitcnt vmcnt(2)
	v_mul_f32_e32 v23, v60, v23
	ds_write2_b32 v24, v22, v23 offset1:66
	s_waitcnt vmcnt(0)
	v_pk_mul_f32 v[20:21], v[18:19], v[20:21]
	s_cbranch_execnz .LBB0_49

; __device__ __forceinline__ void transpose_item(const float* W, int N, bf16* WT, int K, int k0, int n0, int drow0, const float* gk, LAS float* scr, int lane) {
;     ...
; #pragma unroll
;     for (int i = 0; i < 32; ++i) { const int kk = 2 * i + (lane >> 5); float v = wv[i]; if (gk) v *= gk[kk]; scr[kk * 33 + (lane & 31)] = v; }
.LBB0_49:
	s_waitcnt vmcnt(13)
	v_add_u32_e32 v18, v3, v44
	s_and_b64 vcc, exec, s[4:5]
	ds_write2_b32 v18, v20, v21 offset1:66
	s_cbranch_vccnz .LBB0_175
	s_waitcnt vmcnt(12)
	v_lshlrev_b32_e32 v19, 2, v4
	v_mov_b32_e32 v20, v224
	v_mov_b32_e32 v21, v225
	v_mov_b32_e32 v18, v226
	s_nop 0
	v_mov_b32_e32 v19, v227
	v_add_u32_e32 v22, v3, v45
	s_waitcnt vmcnt(3)
	v_mul_f32_e32 v20, v57, v20
	s_waitcnt vmcnt(2)
	v_mul_f32_e32 v21, v58, v21
	ds_write2_b32 v22, v20, v21 offset1:66
	s_waitcnt vmcnt(0)
	v_pk_mul_f32 v[18:19], v[16:17], v[18:19]
	s_cbranch_execnz .LBB0_52

; __device__ __forceinline__ void transpose_item(const float* W, int N, bf16* WT, int K, int k0, int n0, int drow0, const float* gk, LAS float* scr, int lane) {
;     ...
; #pragma unroll
;     for (int i = 0; i < 32; ++i) { const int kk = 2 * i + (lane >> 5); float v = wv[i]; if (gk) v *= gk[kk]; scr[kk * 33 + (lane & 31)] = v; }
.LBB0_52:
	s_waitcnt vmcnt(9)
	v_add_u32_e32 v16, v3, v46
	s_and_b64 vcc, exec, s[4:5]
	ds_write2_b32 v16, v18, v19 offset1:66
	s_cbranch_vccnz .LBB0_176
	s_waitcnt vmcnt(8)
	v_lshlrev_b32_e32 v17, 2, v4
	v_mov_b32_e32 v18, v228
	v_mov_b32_e32 v19, v229
	v_mov_b32_e32 v16, v230
	s_nop 0
	v_mov_b32_e32 v17, v231
	v_add_u32_e32 v20, v3, v47
	s_waitcnt vmcnt(3)
	v_mul_f32_e32 v18, v55, v18
	s_waitcnt vmcnt(2)
	v_mul_f32_e32 v19, v56, v19
	ds_write2_b32 v20, v18, v19 offset1:66
	s_waitcnt vmcnt(0)
	v_pk_mul_f32 v[16:17], v[14:15], v[16:17]
	s_cbranch_execnz .LBB0_55

; __device__ __forceinline__ void transpose_item(const float* W, int N, bf16* WT, int K, int k0, int n0, int drow0, const float* gk, LAS float* scr, int lane) {
;     ...
; #pragma unroll
;     for (int i = 0; i < 32; ++i) { const int kk = 2 * i + (lane >> 5); float v = wv[i]; if (gk) v *= gk[kk]; scr[kk * 33 + (lane & 31)] = v; }
.LBB0_55:
	s_waitcnt vmcnt(5)
	v_add_u32_e32 v14, v3, v47
	ds_write2_b32 v14, v16, v17 offset0:132 offset1:198
	s_and_b64 vcc, exec, s[4:5]
	v_add_u32_e32 v16, 0x400, v14
	s_cbranch_vccnz .LBB0_177
	s_waitcnt vmcnt(4)
	v_lshlrev_b32_e32 v15, 2, v4
	v_mov_b32_e32 v17, v232
	v_mov_b32_e32 v18, v233
	v_mov_b32_e32 v14, v234
	s_nop 0
	v_mov_b32_e32 v15, v235
	s_waitcnt vmcnt(3)
	v_mul_f32_e32 v17, v9, v17
	s_waitcnt vmcnt(2)
	v_mul_f32_e32 v18, v11, v18
	ds_write2_b32 v16, v17, v18 offset0:8 offset1:74
	s_waitcnt vmcnt(0)
	v_pk_mul_f32 v[14:15], v[12:13], v[14:15]
	s_cbranch_execnz .LBB0_58

; #define LAS __attribute__((address_space(3)))
; __device__ __forceinline__ void transpose_item(const float* W, int N, bf16* WT, int K, int k0, int n0, int drow0, const float* gk, LAS float* scr, int lane) {
;     float wv[32];
; #pragma unroll
;     for (int i = 0; i < 32; ++i) wv[i] = W[(size_t)(k0 + 2 * i + (lane >> 5)) * N + n0 + (lane & 31)];
.LBB0_63:
	v_readlane_b32 s52, v250, 11
	s_lshl_b32 s5, s5, 6
	v_readlane_b32 s64, v250, 23
	v_readlane_b32 s65, v250, 24
	s_add_u32 s30, s64, s86
	v_readlane_b32 s62, v250, 21
	s_addc_u32 s31, s65, s85
	v_readlane_b32 s63, v250, 22
	s_add_u32 s28, s62, s24
	s_addc_u32 s29, s63, s25
	s_and_b32 s27, s5, 0xffc0
	s_lshl_b32 s5, s27, 2
	s_add_u32 s28, s28, s5
	s_addc_u32 s29, s29, 0
	s_lshl_b32 s4, s4, 2
	s_add_u32 s4, s30, s4
	v_or_b32_e32 v9, s27, v4
	s_addc_u32 s5, s31, 0
	v_lshl_add_u64 v[12:13], s[4:5], 0, v[6:7]
	v_mul_u32_u24_e32 v14, 0x2c00, v9
	v_mov_b32_e32 v15, v7
	v_lshl_add_u64 v[12:13], v[12:13], 0, v[14:15]
	v_add_co_u32_e32 v14, vcc, s93, v12
	v_readlane_b32 s12, v251, 20
	s_nop 0
	v_addc_co_u32_e32 v15, vcc, 0, v13, vcc
	v_add_co_u32_e32 v16, vcc, s94, v12
	v_readlane_b32 s13, v251, 21
	s_nop 0
	v_addc_co_u32_e32 v17, vcc, 0, v13, vcc
	v_add_co_u32_e32 v18, vcc, s95, v12
	v_readlane_b32 s53, v250, 12
	s_nop 0
	v_addc_co_u32_e32 v19, vcc, 0, v13, vcc
	v_add_co_u32_e32 v20, vcc, s96, v12
	v_readlane_b32 s54, v250, 13
	s_nop 0
	v_addc_co_u32_e32 v21, vcc, 0, v13, vcc
	v_add_co_u32_e32 v22, vcc, s97, v12
	v_readlane_b32 s55, v250, 14
	s_nop 0
	v_addc_co_u32_e32 v23, vcc, 0, v13, vcc
	v_add_co_u32_e32 v24, vcc, s51, v12
	v_readlane_b32 s56, v250, 15
	s_nop 0
	v_addc_co_u32_e32 v25, vcc, 0, v13, vcc
	v_add_co_u32_e32 v28, vcc, s2, v12
	v_readlane_b32 s57, v250, 16
	s_nop 0
	v_addc_co_u32_e32 v29, vcc, 0, v13, vcc
	global_load_dword v68, v[12:13], off
	global_load_dword v67, v[14:15], off offset:2048
	global_load_dword v26, v[16:17], off
	global_load_dword v27, v[18:19], off offset:2048
	global_load_dword v65, v[20:21], off
	global_load_dword v66, v[22:23], off offset:2048
	s_nop 0
	global_load_dword v24, v[24:25], off
	s_nop 0
	global_load_dword v25, v[28:29], off offset:2048
	v_add_co_u32_e32 v14, vcc, s6, v12
	v_readlane_b32 s58, v250, 17
	s_nop 0
	v_addc_co_u32_e32 v15, vcc, 0, v13, vcc
	v_add_co_u32_e32 v16, vcc, s7, v12
	v_readlane_b32 s59, v250, 18
	s_nop 0
	v_addc_co_u32_e32 v17, vcc, 0, v13, vcc
	v_add_co_u32_e32 v18, vcc, s20, v12
	v_readlane_b32 s60, v250, 19
	s_nop 0
	v_addc_co_u32_e32 v19, vcc, 0, v13, vcc
	v_add_co_u32_e32 v20, vcc, s21, v12
	v_readlane_b32 s61, v250, 20
	s_nop 0
	v_addc_co_u32_e32 v21, vcc, 0, v13, vcc
	v_add_co_u32_e32 v28, vcc, s23, v12
	v_readlane_b32 s66, v250, 25
	s_nop 0
	v_addc_co_u32_e32 v29, vcc, 0, v13, vcc
	v_add_co_u32_e32 v56, vcc, s36, v12
	v_readlane_b32 s67, v250, 26
	s_nop 0
	v_addc_co_u32_e32 v57, vcc, 0, v13, vcc
	v_add_co_u32_e32 v58, vcc, s37, v12
	s_nop 1
	v_addc_co_u32_e32 v59, vcc, 0, v13, vcc
	v_add_co_u32_e32 v70, vcc, s68, v12
	s_nop 1
	v_addc_co_u32_e32 v71, vcc, 0, v13, vcc
	global_load_dword v63, v[14:15], off
	global_load_dword v64, v[16:17], off offset:2048
	global_load_dword v22, v[18:19], off
	global_load_dword v23, v[20:21], off offset:2048
	global_load_dword v61, v[28:29], off
	global_load_dword v62, v[56:57], off offset:2048
	s_nop 0
	global_load_dword v20, v[58:59], off
	global_load_dword v21, v[70:71], off offset:2048
	v_add_co_u32_e32 v14, vcc, s69, v12
	s_nop 1
	v_addc_co_u32_e32 v15, vcc, 0, v13, vcc
	v_add_co_u32_e32 v16, vcc, s70, v12
	s_nop 1
	v_addc_co_u32_e32 v17, vcc, 0, v13, vcc
	v_add_co_u32_e32 v18, vcc, s71, v12
	s_nop 1
	v_addc_co_u32_e32 v19, vcc, 0, v13, vcc
	v_add_co_u32_e32 v28, vcc, s72, v12
	s_nop 1
	v_addc_co_u32_e32 v29, vcc, 0, v13, vcc
	v_add_co_u32_e32 v56, vcc, s73, v12
	s_nop 1
	v_addc_co_u32_e32 v57, vcc, 0, v13, vcc
	v_add_co_u32_e32 v70, vcc, s74, v12
	s_nop 1
	v_addc_co_u32_e32 v71, vcc, 0, v13, vcc
	v_add_co_u32_e32 v72, vcc, s75, v12
	s_nop 1
	v_addc_co_u32_e32 v73, vcc, 0, v13, vcc
	v_add_co_u32_e32 v74, vcc, s76, v12
	s_nop 1
	v_addc_co_u32_e32 v75, vcc, 0, v13, vcc
	global_load_dword v59, v[14:15], off
	global_load_dword v60, v[16:17], off offset:2048
	s_nop 0
	global_load_dword v18, v[18:19], off
	s_nop 0
	global_load_dword v19, v[28:29], off offset:2048
	global_load_dword v55, v[56:57], off
	s_nop 0
	global_load_dword v57, v[70:71], off offset:2048
	global_load_dword v16, v[72:73], off
	global_load_dword v17, v[74:75], off offset:2048
	v_add_co_u32_e32 v14, vcc, s77, v12
	s_nop 1
	v_addc_co_u32_e32 v15, vcc, 0, v13, vcc
	v_add_co_u32_e32 v28, vcc, s78, v12
	s_nop 1
	v_addc_co_u32_e32 v29, vcc, 0, v13, vcc
	v_add_co_u32_e32 v70, vcc, s79, v12
	s_nop 1
	v_addc_co_u32_e32 v71, vcc, 0, v13, vcc
	v_add_co_u32_e32 v72, vcc, s80, v12
	s_nop 1
	v_addc_co_u32_e32 v73, vcc, 0, v13, vcc
	v_add_co_u32_e32 v74, vcc, s81, v12
	s_nop 1
	v_addc_co_u32_e32 v75, vcc, 0, v13, vcc
	v_add_co_u32_e32 v76, vcc, 0x9f000, v12
	s_nop 1
	v_addc_co_u32_e32 v77, vcc, 0, v13, vcc
	v_add_co_u32_e32 v78, vcc, 0xa5000, v12
	s_nop 1
	v_addc_co_u32_e32 v79, vcc, 0, v13, vcc
	v_add_co_u32_e32 v80, vcc, 0xaa000, v12
	s_nop 1
	v_addc_co_u32_e32 v81, vcc, 0, v13, vcc
	global_load_dword v56, v[14:15], off
	global_load_dword v58, v[28:29], off offset:2048
	s_nop 0
	global_load_dword v14, v[70:71], off
	global_load_dword v15, v[72:73], off offset:2048
	global_load_dword v9, v[74:75], off
	global_load_dword v11, v[76:77], off offset:2048
	global_load_dword v12, v[78:79], off
	global_load_dword v13, v[80:81], off offset:2048
	v_cndmask_b32_e64 v28, 0, 1, s[12:13]
	v_cmp_ne_u32_e64 s[4:5], 1, v28
	s_andn2_b64 vcc, exec, s[12:13]
	s_cbranch_vccnz .LBB0_162
; __device__ __forceinline__ void lds_wait() { asm volatile("s_waitcnt lgkmcnt(0)" ::: "memory"); }
; __device__ __forceinline__ void transpose_item(const float* W, int N, bf16* WT, int K, int k0, int n0, int drow0, const float* gk, LAS float* scr, int lane) {
;     ...
;     for (int i = 0; i < 32; ++i) wv[i] = W[(size_t)(k0 + 2 * i + (lane >> 5)) * N + n0 + (lane & 31)];
; #pragma unroll
;     for (int i = 0; i < 32; ++i) { const int kk = 2 * i + (lane >> 5); float v = wv[i]; if (gk) v *= gk[kk]; scr[kk * 33 + (lane & 31)] = v; }
;     lds_wait();
	v_lshlrev_b32_e32 v29, 2, v4
	s_waitcnt vmcnt(32)
	global_load_dword v204, v29, s[28:29]
	global_load_dword v205, v29, s[28:29] offset:8
	global_load_dword v206, v29, s[28:29] offset:16
	global_load_dword v207, v29, s[28:29] offset:24
	global_load_dword v208, v29, s[28:29] offset:32
	global_load_dword v209, v29, s[28:29] offset:40
	global_load_dword v210, v29, s[28:29] offset:48
	global_load_dword v211, v29, s[28:29] offset:56
	global_load_dword v212, v29, s[28:29] offset:64
	global_load_dword v213, v29, s[28:29] offset:72
	global_load_dword v214, v29, s[28:29] offset:80
	global_load_dword v215, v29, s[28:29] offset:88
	global_load_dword v216, v29, s[28:29] offset:96
	global_load_dword v217, v29, s[28:29] offset:104
	global_load_dword v218, v29, s[28:29] offset:112
	global_load_dword v219, v29, s[28:29] offset:120
	global_load_dword v220, v29, s[28:29] offset:128
	global_load_dword v221, v29, s[28:29] offset:136
	global_load_dword v222, v29, s[28:29] offset:144
	global_load_dword v223, v29, s[28:29] offset:152
	global_load_dword v224, v29, s[28:29] offset:160
	global_load_dword v225, v29, s[28:29] offset:168
	global_load_dword v226, v29, s[28:29] offset:176
	global_load_dword v227, v29, s[28:29] offset:184
	global_load_dword v228, v29, s[28:29] offset:192
	global_load_dword v229, v29, s[28:29] offset:200
	global_load_dword v230, v29, s[28:29] offset:208
	global_load_dword v231, v29, s[28:29] offset:216
	global_load_dword v232, v29, s[28:29] offset:224
	global_load_dword v233, v29, s[28:29] offset:232
	global_load_dword v234, v29, s[28:29] offset:240
	s_waitcnt vmcnt(62)
	global_load_dword v235, v29, s[28:29] offset:248
	s_waitcnt vmcnt(0)
	v_mov_b32_e32 v69, v204
	v_mov_b32_e32 v70, v205
	v_mov_b32_e32 v28, v206
	s_nop 0
	v_mov_b32_e32 v29, v207
	v_add_u32_e32 v71, v3, v35
	s_waitcnt vmcnt(3)
	v_mul_f32_e32 v69, v68, v69
	s_waitcnt vmcnt(2)
	v_mul_f32_e32 v70, v67, v70
	ds_write_b32 v5, v69
	ds_write_b32 v71, v70
	s_waitcnt vmcnt(0)
	v_pk_mul_f32 v[28:29], v[26:27], v[28:29]
	s_cbranch_execnz .LBB0_66

; __device__ __forceinline__ void transpose_item(const float* W, int N, bf16* WT, int K, int k0, int n0, int drow0, const float* gk, LAS float* scr, int lane) {
;     ...
; #pragma unroll
;     for (int i = 0; i < 32; ++i) { const int kk = 2 * i + (lane >> 5); float v = wv[i]; if (gk) v *= gk[kk]; scr[kk * 33 + (lane & 31)] = v; }
.LBB0_66:
	s_waitcnt vmcnt(29)
	v_add_u32_e32 v26, v3, v36
	s_and_b64 vcc, exec, s[4:5]
	ds_write2_b32 v26, v28, v29 offset1:66
	s_cbranch_vccnz .LBB0_163
	s_waitcnt vmcnt(28)
	v_lshlrev_b32_e32 v27, 2, v4
	v_mov_b32_e32 v28, v208
	v_mov_b32_e32 v29, v209
	v_mov_b32_e32 v26, v210
	s_nop 0
	v_mov_b32_e32 v27, v211
	v_add_u32_e32 v67, v3, v37
	s_waitcnt vmcnt(3)
	v_mul_f32_e32 v28, v65, v28
	s_waitcnt vmcnt(2)
	v_mul_f32_e32 v29, v66, v29
	ds_write2_b32 v67, v28, v29 offset1:66
	s_waitcnt vmcnt(0)
	v_pk_mul_f32 v[26:27], v[24:25], v[26:27]
	s_cbranch_execnz .LBB0_69

; __device__ __forceinline__ void transpose_item(const float* W, int N, bf16* WT, int K, int k0, int n0, int drow0, const float* gk, LAS float* scr, int lane) {
;     ...
; #pragma unroll
;     for (int i = 0; i < 32; ++i) { const int kk = 2 * i + (lane >> 5); float v = wv[i]; if (gk) v *= gk[kk]; scr[kk * 33 + (lane & 31)] = v; }
.LBB0_78:
	s_waitcnt vmcnt(13)
	v_add_u32_e32 v18, v3, v44
	s_and_b64 vcc, exec, s[4:5]
	ds_write2_b32 v18, v20, v21 offset1:66
	s_cbranch_vccnz .LBB0_167
	s_waitcnt vmcnt(12)
	v_lshlrev_b32_e32 v19, 2, v4
	v_mov_b32_e32 v20, v224
	v_mov_b32_e32 v21, v225
	v_mov_b32_e32 v18, v226
	s_nop 0
	v_mov_b32_e32 v19, v227
	v_add_u32_e32 v22, v3, v45
	s_waitcnt vmcnt(3)
	v_mul_f32_e32 v20, v55, v20
	s_waitcnt vmcnt(2)
	v_mul_f32_e32 v21, v57, v21
	ds_write2_b32 v22, v20, v21 offset1:66
	s_waitcnt vmcnt(0)
	v_pk_mul_f32 v[18:19], v[16:17], v[18:19]
	s_cbranch_execnz .LBB0_81

; __device__ __forceinline__ void transpose_item(const float* W, int N, bf16* WT, int K, int k0, int n0, int drow0, const float* gk, LAS float* scr, int lane) {
;     ...
; #pragma unroll
;     for (int i = 0; i < 32; ++i) { const int kk = 2 * i + (lane >> 5); float v = wv[i]; if (gk) v *= gk[kk]; scr[kk * 33 + (lane & 31)] = v; }
.LBB0_81:
	s_waitcnt vmcnt(9)
	v_add_u32_e32 v16, v3, v46
	s_and_b64 vcc, exec, s[4:5]
	ds_write2_b32 v16, v18, v19 offset1:66
	s_cbranch_vccnz .LBB0_168
	s_waitcnt vmcnt(8)
	v_lshlrev_b32_e32 v17, 2, v4
	v_mov_b32_e32 v18, v228
	v_mov_b32_e32 v19, v229
	v_mov_b32_e32 v16, v230
	s_nop 0
	v_mov_b32_e32 v17, v231
	v_add_u32_e32 v20, v3, v47
	s_waitcnt vmcnt(3)
	v_mul_f32_e32 v18, v56, v18
	s_waitcnt vmcnt(2)
	v_mul_f32_e32 v19, v58, v19
	ds_write2_b32 v20, v18, v19 offset1:66
	s_waitcnt vmcnt(0)
	v_pk_mul_f32 v[16:17], v[14:15], v[16:17]
	s_cbranch_execnz .LBB0_84

; __device__ __forceinline__ void transpose_item(const float* W, int N, bf16* WT, int K, int k0, int n0, int drow0, const float* gk, LAS float* scr, int lane) {
;     ...
;     for (int i = 0; i < 32; ++i) wv[i] = W[(size_t)(k0 + 2 * i + (lane >> 5)) * N + n0 + (lane & 31)];
; __device__ __forceinline__ void p0_weight_item(const Args& a, int l, int r, LAS float* scr, int lane) {
;     ...
;         if (r < 2 * IT_BIG) { const int up = r >= IT_BIG; const int it = r - up * IT_BIG; const int kb = it / 88, nb = it % 88, k0 = 64 * kb, n0 = 32 * nb;
;             const float* W = a.in[(f ? 29 : 2) + up] + (size_t)l * DM * FF;
;             transpose_item(W, FF, gu, DM, k0, n0, (n0 >> 7) * 256 + up * 128 + (n0 & 127), nrm + k0, scr, lane); return; }
.LBB0_92:
	s_andn2_b64 vcc, exec, s[4:5]
	s_cbranch_vccnz .LBB0_118
	v_readlane_b32 s52, v250, 59
	v_readlane_b32 s60, v251, 3
	v_readlane_b32 s61, v251, 4
	s_add_u32 s27, s60, s24
	s_addc_u32 s35, s61, s25
	s_cmpk_gt_u32 s88, 0x15ff
	s_cselect_b64 s[28:29], -1, 0
	s_and_b64 s[4:5], s[28:29], exec
	v_readlane_b32 s62, v251, 5
	v_readlane_b32 s63, v251, 6
	v_readlane_b32 s64, v251, 7
	v_readlane_b32 s65, v251, 8
	s_cselect_b32 s4, 0xfa80, 0
	s_cselect_b32 s5, s64, s62
	s_cselect_b32 s31, s65, s63
	s_sub_i32 s4, s4, s87
	s_add_i32 s4, s82, s4
	s_addk_i32 s4, 0xef80
	s_sext_i32_i16 s22, s4
	s_mulk_i32 s22, 0xba3
	s_lshr_b32 s30, s22, 31
	s_ashr_i32 s22, s22, 18
	s_add_i32 s30, s22, s30
	s_mul_i32 s22, s30, 0x58
	s_sub_i32 s4, s4, s22
	s_sext_i32_i16 s22, s4
	s_lshl_b32 s30, s30, 6
	s_lshl_b32 s34, s22, 5
	s_add_u32 s40, s5, s86
	s_addc_u32 s41, s31, s85
	s_ashr_i32 s31, s30, 31
	s_lshl_b64 s[4:5], s[30:31], 2
	s_add_u32 s38, s27, s4
	s_addc_u32 s39, s35, s5
	s_ashr_i32 s35, s34, 31
	s_lshl_b64 s[4:5], s[34:35], 2
	v_or_b32_e32 v9, s30, v4
	s_add_u32 s4, s40, s4
	s_addc_u32 s5, s41, s5
	v_mul_i32_i24_e32 v14, 0x2c00, v9
	v_lshl_add_u64 v[12:13], s[4:5], 0, v[6:7]
	v_ashrrev_i32_e32 v15, 31, v14
	v_lshl_add_u64 v[12:13], v[12:13], 0, v[14:15]
	v_add_co_u32_e32 v14, vcc, s93, v12
	v_readlane_b32 s53, v250, 60
	s_nop 0
	v_addc_co_u32_e32 v15, vcc, 0, v13, vcc
	v_add_co_u32_e32 v16, vcc, s94, v12
	v_readlane_b32 s54, v250, 61
	s_nop 0
	v_addc_co_u32_e32 v17, vcc, 0, v13, vcc
	v_add_co_u32_e32 v18, vcc, s95, v12
	v_readlane_b32 s55, v250, 62
	s_nop 0
	v_addc_co_u32_e32 v19, vcc, 0, v13, vcc
	v_add_co_u32_e32 v20, vcc, s96, v12
	v_readlane_b32 s56, v250, 63
	s_nop 0
	v_addc_co_u32_e32 v21, vcc, 0, v13, vcc
	v_add_co_u32_e32 v22, vcc, s97, v12
	v_readlane_b32 s57, v251, 0
	s_nop 0
	v_addc_co_u32_e32 v23, vcc, 0, v13, vcc
	v_add_co_u32_e32 v24, vcc, s51, v12
	v_readlane_b32 s58, v251, 1
	s_nop 0
	v_addc_co_u32_e32 v25, vcc, 0, v13, vcc
	v_add_co_u32_e32 v28, vcc, s2, v12
	v_readlane_b32 s59, v251, 2
	s_nop 0
	v_addc_co_u32_e32 v29, vcc, 0, v13, vcc
	global_load_dword v68, v[12:13], off
	global_load_dword v67, v[14:15], off offset:2048
	global_load_dword v26, v[16:17], off
	global_load_dword v27, v[18:19], off offset:2048
	global_load_dword v65, v[20:21], off
	global_load_dword v66, v[22:23], off offset:2048
	s_nop 0
	global_load_dword v24, v[24:25], off
	s_nop 0
	global_load_dword v25, v[28:29], off offset:2048
	v_add_co_u32_e32 v14, vcc, s6, v12
	v_readlane_b32 s66, v251, 9
	s_nop 0
	v_addc_co_u32_e32 v15, vcc, 0, v13, vcc
	v_add_co_u32_e32 v16, vcc, s7, v12
	v_readlane_b32 s67, v251, 10
	s_nop 0
	v_addc_co_u32_e32 v17, vcc, 0, v13, vcc
	v_add_co_u32_e32 v18, vcc, s20, v12
	s_nop 1
	v_addc_co_u32_e32 v19, vcc, 0, v13, vcc
	v_add_co_u32_e32 v20, vcc, s21, v12
	s_nop 1
	v_addc_co_u32_e32 v21, vcc, 0, v13, vcc
	v_add_co_u32_e32 v28, vcc, s23, v12
	s_nop 1
	v_addc_co_u32_e32 v29, vcc, 0, v13, vcc
	v_add_co_u32_e32 v56, vcc, s36, v12
	s_nop 1
	v_addc_co_u32_e32 v57, vcc, 0, v13, vcc
	v_add_co_u32_e32 v58, vcc, s37, v12
	s_nop 1
	v_addc_co_u32_e32 v59, vcc, 0, v13, vcc
	v_add_co_u32_e32 v70, vcc, s68, v12
	s_nop 1
	v_addc_co_u32_e32 v71, vcc, 0, v13, vcc
	global_load_dword v63, v[14:15], off
	global_load_dword v64, v[16:17], off offset:2048
	global_load_dword v22, v[18:19], off
	global_load_dword v23, v[20:21], off offset:2048
	global_load_dword v61, v[28:29], off
	global_load_dword v62, v[56:57], off offset:2048
	s_nop 0
	global_load_dword v20, v[58:59], off
	global_load_dword v21, v[70:71], off offset:2048
	v_add_co_u32_e32 v14, vcc, s69, v12
	s_nop 1
	v_addc_co_u32_e32 v15, vcc, 0, v13, vcc
	v_add_co_u32_e32 v16, vcc, s70, v12
	s_nop 1
	v_addc_co_u32_e32 v17, vcc, 0, v13, vcc
	v_add_co_u32_e32 v18, vcc, s71, v12
	s_nop 1
	v_addc_co_u32_e32 v19, vcc, 0, v13, vcc
	v_add_co_u32_e32 v28, vcc, s72, v12
	s_nop 1
	v_addc_co_u32_e32 v29, vcc, 0, v13, vcc
	v_add_co_u32_e32 v56, vcc, s73, v12
	s_nop 1
	v_addc_co_u32_e32 v57, vcc, 0, v13, vcc
	v_add_co_u32_e32 v70, vcc, s74, v12
	s_nop 1
	v_addc_co_u32_e32 v71, vcc, 0, v13, vcc
	v_add_co_u32_e32 v72, vcc, s75, v12
	s_nop 1
	v_addc_co_u32_e32 v73, vcc, 0, v13, vcc
	v_add_co_u32_e32 v74, vcc, s76, v12
	s_nop 1
	v_addc_co_u32_e32 v75, vcc, 0, v13, vcc
	global_load_dword v59, v[14:15], off
	global_load_dword v60, v[16:17], off offset:2048
	s_nop 0
	global_load_dword v18, v[18:19], off
	s_nop 0
	global_load_dword v19, v[28:29], off offset:2048
	global_load_dword v55, v[56:57], off
	s_nop 0
	global_load_dword v57, v[70:71], off offset:2048
	global_load_dword v16, v[72:73], off
	global_load_dword v17, v[74:75], off offset:2048
	v_add_co_u32_e32 v14, vcc, s77, v12
	s_nop 1
	v_addc_co_u32_e32 v15, vcc, 0, v13, vcc
	v_add_co_u32_e32 v28, vcc, s78, v12
	s_nop 1
	v_addc_co_u32_e32 v29, vcc, 0, v13, vcc
	v_add_co_u32_e32 v70, vcc, s79, v12
	s_nop 1
	v_addc_co_u32_e32 v71, vcc, 0, v13, vcc
	v_add_co_u32_e32 v72, vcc, s80, v12
	s_nop 1
	v_addc_co_u32_e32 v73, vcc, 0, v13, vcc
	v_add_co_u32_e32 v74, vcc, s81, v12
	s_nop 1
	v_addc_co_u32_e32 v75, vcc, 0, v13, vcc
	v_add_co_u32_e32 v76, vcc, 0x9f000, v12
	s_nop 1
	v_addc_co_u32_e32 v77, vcc, 0, v13, vcc
	v_add_co_u32_e32 v78, vcc, 0xa5000, v12
	s_nop 1
	v_addc_co_u32_e32 v79, vcc, 0, v13, vcc
	v_add_co_u32_e32 v80, vcc, 0xaa000, v12
	s_nop 1
	v_addc_co_u32_e32 v81, vcc, 0, v13, vcc
	global_load_dword v56, v[14:15], off
	global_load_dword v58, v[28:29], off offset:2048
	s_nop 0
	global_load_dword v14, v[70:71], off
	global_load_dword v15, v[72:73], off offset:2048
	global_load_dword v9, v[74:75], off
	global_load_dword v11, v[76:77], off offset:2048
	global_load_dword v12, v[78:79], off
	global_load_dword v13, v[80:81], off offset:2048
	v_cndmask_b32_e64 v28, 0, 1, s[8:9]
	v_cmp_ne_u32_e64 s[4:5], 1, v28
	s_andn2_b64 vcc, exec, s[8:9]
	s_cbranch_vccnz .LBB0_154
; __device__ __forceinline__ void transpose_item(const float* W, int N, bf16* WT, int K, int k0, int n0, int drow0, const float* gk, LAS float* scr, int lane) {
;     ...
;     for (int i = 0; i < 32; ++i) wv[i] = W[(size_t)(k0 + 2 * i + (lane >> 5)) * N + n0 + (lane & 31)];
; #pragma unroll
;     for (int i = 0; i < 32; ++i) { const int kk = 2 * i + (lane >> 5); float v = wv[i]; if (gk) v *= gk[kk]; scr[kk * 33 + (lane & 31)] = v; }
	v_lshlrev_b32_e32 v29, 2, v4
	s_waitcnt vmcnt(32)
	global_load_dword v204, v29, s[38:39]
	global_load_dword v205, v29, s[38:39] offset:8
	global_load_dword v206, v29, s[38:39] offset:16
	global_load_dword v207, v29, s[38:39] offset:24
	global_load_dword v208, v29, s[38:39] offset:32
	global_load_dword v209, v29, s[38:39] offset:40
	global_load_dword v210, v29, s[38:39] offset:48
	global_load_dword v211, v29, s[38:39] offset:56
	global_load_dword v212, v29, s[38:39] offset:64
	global_load_dword v213, v29, s[38:39] offset:72
	global_load_dword v214, v29, s[38:39] offset:80
	global_load_dword v215, v29, s[38:39] offset:88
	global_load_dword v216, v29, s[38:39] offset:96
	global_load_dword v217, v29, s[38:39] offset:104
	global_load_dword v218, v29, s[38:39] offset:112
	global_load_dword v219, v29, s[38:39] offset:120
	global_load_dword v220, v29, s[38:39] offset:128
	global_load_dword v221, v29, s[38:39] offset:136
	global_load_dword v222, v29, s[38:39] offset:144
	global_load_dword v223, v29, s[38:39] offset:152
	global_load_dword v224, v29, s[38:39] offset:160
	global_load_dword v225, v29, s[38:39] offset:168
	global_load_dword v226, v29, s[38:39] offset:176
	global_load_dword v227, v29, s[38:39] offset:184
	global_load_dword v228, v29, s[38:39] offset:192
	global_load_dword v229, v29, s[38:39] offset:200
	global_load_dword v230, v29, s[38:39] offset:208
	global_load_dword v231, v29, s[38:39] offset:216
	global_load_dword v232, v29, s[38:39] offset:224
	global_load_dword v233, v29, s[38:39] offset:232
	global_load_dword v234, v29, s[38:39] offset:240
	s_waitcnt vmcnt(62)
	global_load_dword v235, v29, s[38:39] offset:248
	s_waitcnt vmcnt(0)
	v_mov_b32_e32 v69, v204
	v_mov_b32_e32 v70, v205
	v_mov_b32_e32 v28, v206
	s_nop 0
	v_mov_b32_e32 v29, v207
	v_add_u32_e32 v71, v3, v35
	s_waitcnt vmcnt(3)
	v_mul_f32_e32 v69, v68, v69
	s_waitcnt vmcnt(2)
	v_mul_f32_e32 v70, v67, v70
	ds_write_b32 v5, v69
	ds_write_b32 v71, v70
	s_waitcnt vmcnt(0)
	v_pk_mul_f32 v[28:29], v[26:27], v[28:29]
	s_cbranch_execnz .LBB0_96

; __device__ __forceinline__ void transpose_item(const float* W, int N, bf16* WT, int K, int k0, int n0, int drow0, const float* gk, LAS float* scr, int lane) {
;     ...
;     for (int i = 0; i < 32; ++i) wv[i] = W[(size_t)(k0 + 2 * i + (lane >> 5)) * N + n0 + (lane & 31)];
; __device__ __forceinline__ void p0_weight_item(const Args& a, int l, int r, LAS float* scr, int lane) {
;     ...
;         if (r < 2 * IT_BIG) { const int up = r >= IT_BIG; const int it = r - up * IT_BIG; const int kb = it / 88, nb = it % 88, k0 = 64 * kb, n0 = 32 * nb;
;             const float* W = a.in[(f ? 29 : 2) + up] + (size_t)l * DM * FF;
;             transpose_item(W, FF, gu, DM, k0, n0, (n0 >> 7) * 256 + up * 128 + (n0 & 127), nrm + k0, scr, lane); return; }
.LBB0_122:
	s_andn2_b64 vcc, exec, s[4:5]
	s_cbranch_vccnz .LBB0_9
	v_readlane_b32 s52, v250, 11
	v_readlane_b32 s54, v250, 13
	v_readlane_b32 s55, v250, 14
	s_add_u32 s29, s54, s24
	s_addc_u32 s31, s55, s25
	s_cmpk_gt_i32 s88, 0x57f
	s_cselect_b64 s[24:25], -1, 0
	s_and_b64 s[4:5], s[24:25], exec
	v_readlane_b32 s56, v250, 15
	v_readlane_b32 s57, v250, 16
	v_readlane_b32 s58, v250, 17
	v_readlane_b32 s59, v250, 18
	s_cselect_b32 s4, 0xfa80, 0
	s_cselect_b32 s5, s59, s57
	s_cselect_b32 s27, s58, s56
	s_sub_i32 s4, s4, s87
	s_add_i32 s4, s82, s4
	s_sext_i32_i16 s22, s4
	s_mulk_i32 s22, 0xba3
	s_lshr_b32 s26, s22, 31
	s_ashr_i32 s22, s22, 18
	s_add_i32 s26, s22, s26
	s_mul_i32 s22, s26, 0x58
	s_sub_i32 s4, s4, s22
	s_sext_i32_i16 s22, s4
	s_lshl_b32 s26, s26, 6
	s_lshl_b32 s28, s22, 5
	s_add_u32 s34, s27, s86
	s_addc_u32 s35, s5, s85
	s_ashr_i32 s27, s26, 31
	s_lshl_b64 s[4:5], s[26:27], 2
	s_add_u32 s30, s29, s4
	s_addc_u32 s31, s31, s5
	s_ashr_i32 s29, s28, 31
	s_lshl_b64 s[4:5], s[28:29], 2
	v_or_b32_e32 v9, s26, v4
	s_add_u32 s4, s34, s4
	s_addc_u32 s5, s35, s5
	v_mul_i32_i24_e32 v14, 0x2c00, v9
	v_lshl_add_u64 v[12:13], s[4:5], 0, v[6:7]
	v_ashrrev_i32_e32 v15, 31, v14
	v_lshl_add_u64 v[12:13], v[12:13], 0, v[14:15]
	v_add_co_u32_e32 v14, vcc, s93, v12
	v_readlane_b32 s53, v250, 12
	s_nop 0
	v_addc_co_u32_e32 v15, vcc, 0, v13, vcc
	v_add_co_u32_e32 v16, vcc, s94, v12
	v_readlane_b32 s60, v250, 19
	s_nop 0
	v_addc_co_u32_e32 v17, vcc, 0, v13, vcc
	v_add_co_u32_e32 v18, vcc, s95, v12
	v_readlane_b32 s61, v250, 20
	s_nop 0
	v_addc_co_u32_e32 v19, vcc, 0, v13, vcc
	v_add_co_u32_e32 v20, vcc, s96, v12
	v_readlane_b32 s62, v250, 21
	s_nop 0
	v_addc_co_u32_e32 v21, vcc, 0, v13, vcc
	v_add_co_u32_e32 v22, vcc, s97, v12
	v_readlane_b32 s63, v250, 22
	s_nop 0
	v_addc_co_u32_e32 v23, vcc, 0, v13, vcc
	v_add_co_u32_e32 v24, vcc, s51, v12
	v_readlane_b32 s64, v250, 23
	s_nop 0
	v_addc_co_u32_e32 v25, vcc, 0, v13, vcc
	v_add_co_u32_e32 v28, vcc, s2, v12
	v_readlane_b32 s65, v250, 24
	s_nop 0
	v_addc_co_u32_e32 v29, vcc, 0, v13, vcc
	global_load_dword v68, v[12:13], off
	global_load_dword v69, v[14:15], off offset:2048
	global_load_dword v26, v[16:17], off
	global_load_dword v27, v[18:19], off offset:2048
	global_load_dword v66, v[20:21], off
	global_load_dword v67, v[22:23], off offset:2048
	s_nop 0
	global_load_dword v24, v[24:25], off
	s_nop 0
	global_load_dword v25, v[28:29], off offset:2048
	v_add_co_u32_e32 v14, vcc, s6, v12
	v_readlane_b32 s66, v250, 25
	s_nop 0
	v_addc_co_u32_e32 v15, vcc, 0, v13, vcc
	v_add_co_u32_e32 v16, vcc, s7, v12
	v_readlane_b32 s67, v250, 26
	s_nop 0
	v_addc_co_u32_e32 v17, vcc, 0, v13, vcc
	v_add_co_u32_e32 v18, vcc, s20, v12
	s_nop 1
	v_addc_co_u32_e32 v19, vcc, 0, v13, vcc
	v_add_co_u32_e32 v20, vcc, s21, v12
	s_nop 1
	v_addc_co_u32_e32 v21, vcc, 0, v13, vcc
	v_add_co_u32_e32 v28, vcc, s23, v12
	s_nop 1
	v_addc_co_u32_e32 v29, vcc, 0, v13, vcc
	v_add_co_u32_e32 v56, vcc, s36, v12
	s_nop 1
	v_addc_co_u32_e32 v57, vcc, 0, v13, vcc
	v_add_co_u32_e32 v58, vcc, s37, v12
	s_nop 1
	v_addc_co_u32_e32 v59, vcc, 0, v13, vcc
	v_add_co_u32_e32 v60, vcc, s68, v12
	s_nop 1
	v_addc_co_u32_e32 v61, vcc, 0, v13, vcc
	global_load_dword v64, v[14:15], off
	global_load_dword v65, v[16:17], off offset:2048
	global_load_dword v22, v[18:19], off
	global_load_dword v23, v[20:21], off offset:2048
	global_load_dword v62, v[28:29], off
	global_load_dword v63, v[56:57], off offset:2048
	s_nop 0
	global_load_dword v20, v[58:59], off
	global_load_dword v21, v[60:61], off offset:2048
	v_add_co_u32_e32 v14, vcc, s69, v12
	s_nop 1
	v_addc_co_u32_e32 v15, vcc, 0, v13, vcc
	v_add_co_u32_e32 v16, vcc, s70, v12
	s_nop 1
	v_addc_co_u32_e32 v17, vcc, 0, v13, vcc
	v_add_co_u32_e32 v18, vcc, s71, v12
	s_nop 1
	v_addc_co_u32_e32 v19, vcc, 0, v13, vcc
	v_add_co_u32_e32 v28, vcc, s72, v12
	s_nop 1
	v_addc_co_u32_e32 v29, vcc, 0, v13, vcc
	v_add_co_u32_e32 v56, vcc, s73, v12
	s_nop 1
	v_addc_co_u32_e32 v57, vcc, 0, v13, vcc
	v_add_co_u32_e32 v58, vcc, s74, v12
	s_nop 1
	v_addc_co_u32_e32 v59, vcc, 0, v13, vcc
	v_add_co_u32_e32 v70, vcc, s75, v12
	s_nop 1
	v_addc_co_u32_e32 v71, vcc, 0, v13, vcc
	v_add_co_u32_e32 v72, vcc, s76, v12
	s_nop 1
	v_addc_co_u32_e32 v73, vcc, 0, v13, vcc
	global_load_dword v60, v[14:15], off
	global_load_dword v61, v[16:17], off offset:2048
	s_nop 0
	global_load_dword v18, v[18:19], off
	s_nop 0
	global_load_dword v19, v[28:29], off offset:2048
	global_load_dword v55, v[56:57], off
	s_nop 0
	global_load_dword v56, v[58:59], off offset:2048
	global_load_dword v14, v[70:71], off
	global_load_dword v15, v[72:73], off offset:2048
	v_add_co_u32_e32 v16, vcc, s77, v12
	v_lshlrev_b32_e32 v57, 2, v4
	s_nop 0
	v_addc_co_u32_e32 v17, vcc, 0, v13, vcc
	v_add_co_u32_e32 v28, vcc, s78, v12
	s_nop 1
	v_addc_co_u32_e32 v29, vcc, 0, v13, vcc
	v_add_co_u32_e32 v70, vcc, s79, v12
	s_nop 1
	v_addc_co_u32_e32 v71, vcc, 0, v13, vcc
	v_add_co_u32_e32 v72, vcc, s80, v12
	s_nop 1
	v_addc_co_u32_e32 v73, vcc, 0, v13, vcc
	v_add_co_u32_e32 v74, vcc, s81, v12
	s_nop 1
	v_addc_co_u32_e32 v75, vcc, 0, v13, vcc
	v_add_co_u32_e32 v76, vcc, 0x9f000, v12
	s_nop 1
	v_addc_co_u32_e32 v77, vcc, 0, v13, vcc
	v_add_co_u32_e32 v78, vcc, 0xa5000, v12
	s_nop 1
	v_addc_co_u32_e32 v79, vcc, 0, v13, vcc
	v_add_co_u32_e32 v80, vcc, 0xaa000, v12
	s_nop 1
	v_addc_co_u32_e32 v81, vcc, 0, v13, vcc
	global_load_dword v58, v[16:17], off
	global_load_dword v59, v[28:29], off offset:2048
	s_nop 0
	global_load_dword v16, v[70:71], off
	global_load_dword v17, v[72:73], off offset:2048
	global_load_dword v9, v[74:75], off
	global_load_dword v11, v[76:77], off offset:2048
	global_load_dword v12, v[78:79], off
	global_load_dword v13, v[80:81], off offset:2048
	v_cndmask_b32_e64 v28, 0, 1, s[10:11]
	v_cmp_ne_u32_e64 s[4:5], 1, v28
	s_andn2_b64 vcc, exec, s[10:11]
	v_add_u32_e32 v70, v3, v35
	s_cbranch_vccnz .LBB0_146
; __device__ __forceinline__ void transpose_item(const float* W, int N, bf16* WT, int K, int k0, int n0, int drow0, const float* gk, LAS float* scr, int lane) {
;     ...
;     for (int i = 0; i < 32; ++i) wv[i] = W[(size_t)(k0 + 2 * i + (lane >> 5)) * N + n0 + (lane & 31)];
; #pragma unroll
;     for (int i = 0; i < 32; ++i) { const int kk = 2 * i + (lane >> 5); float v = wv[i]; if (gk) v *= gk[kk]; scr[kk * 33 + (lane & 31)] = v; }
	s_waitcnt vmcnt(32)
	global_load_dword v204, v57, s[30:31]
	global_load_dword v205, v57, s[30:31] offset:8
	global_load_dword v206, v57, s[30:31] offset:16
	global_load_dword v207, v57, s[30:31] offset:24
	global_load_dword v208, v57, s[30:31] offset:32
	global_load_dword v209, v57, s[30:31] offset:40
	global_load_dword v210, v57, s[30:31] offset:48
	global_load_dword v211, v57, s[30:31] offset:56
	global_load_dword v212, v57, s[30:31] offset:64
	global_load_dword v213, v57, s[30:31] offset:72
	global_load_dword v214, v57, s[30:31] offset:80
	global_load_dword v215, v57, s[30:31] offset:88
	global_load_dword v216, v57, s[30:31] offset:96
	global_load_dword v217, v57, s[30:31] offset:104
	global_load_dword v218, v57, s[30:31] offset:112
	global_load_dword v219, v57, s[30:31] offset:120
	global_load_dword v220, v57, s[30:31] offset:128
	global_load_dword v221, v57, s[30:31] offset:136
	global_load_dword v222, v57, s[30:31] offset:144
	global_load_dword v223, v57, s[30:31] offset:152
	global_load_dword v224, v57, s[30:31] offset:160
	global_load_dword v225, v57, s[30:31] offset:168
	global_load_dword v226, v57, s[30:31] offset:176
	global_load_dword v227, v57, s[30:31] offset:184
	global_load_dword v228, v57, s[30:31] offset:192
	global_load_dword v229, v57, s[30:31] offset:200
	global_load_dword v230, v57, s[30:31] offset:208
	global_load_dword v231, v57, s[30:31] offset:216
	global_load_dword v232, v57, s[30:31] offset:224
	global_load_dword v233, v57, s[30:31] offset:232
	global_load_dword v234, v57, s[30:31] offset:240
	s_waitcnt vmcnt(62)
	global_load_dword v235, v57, s[30:31] offset:248
	s_waitcnt vmcnt(0)
	v_mov_b32_e32 v71, v204
	v_mov_b32_e32 v72, v205
	v_mov_b32_e32 v28, v206
	v_mov_b32_e32 v29, v207
	s_waitcnt vmcnt(3)
	v_mul_f32_e32 v71, v68, v71
	s_waitcnt vmcnt(2)
	v_mul_f32_e32 v72, v69, v72
	ds_write_b32 v5, v71
	ds_write_b32 v70, v72
	s_waitcnt vmcnt(0)
	v_pk_mul_f32 v[28:29], v[26:27], v[28:29]
	s_cbranch_execnz .LBB0_126

; __device__ __forceinline__ void transpose_item(const float* W, int N, bf16* WT, int K, int k0, int n0, int drow0, const float* gk, LAS float* scr, int lane) {
;     ...
;     for (int i = 0; i < 32; ++i) { const int kk = 2 * i + (lane >> 5); float v = wv[i]; if (gk) v *= gk[kk]; scr[kk * 33 + (lane & 31)] = v; }
.LBB0_126:
	s_waitcnt vmcnt(29)
	v_add_u32_e32 v26, v3, v36
	ds_write2_b32 v26, v28, v29 offset1:66
	s_and_b64 vcc, exec, s[4:5]
	v_add_u32_e32 v28, v3, v37
	s_cbranch_vccnz .LBB0_147
	v_mov_b32_e32 v29, v208
	v_mov_b32_e32 v68, v209
	v_mov_b32_e32 v26, v210
	v_mov_b32_e32 v27, v211
	s_waitcnt vmcnt(3)
	v_mul_f32_e32 v29, v66, v29
	s_waitcnt vmcnt(2)
	v_mul_f32_e32 v68, v67, v68
	ds_write2_b32 v28, v29, v68 offset1:66
	s_waitcnt vmcnt(0)
	v_pk_mul_f32 v[26:27], v[24:25], v[26:27]
	s_cbranch_execnz .LBB0_129

; __device__ __forceinline__ void transpose_item(const float* W, int N, bf16* WT, int K, int k0, int n0, int drow0, const float* gk, LAS float* scr, int lane) {
;     ...
;     for (int i = 0; i < 32; ++i) { const int kk = 2 * i + (lane >> 5); float v = wv[i]; if (gk) v *= gk[kk]; scr[kk * 33 + (lane & 31)] = v; }
.LBB0_129:
	s_waitcnt vmcnt(25)
	v_add_u32_e32 v24, v3, v38
	ds_write2_b32 v24, v26, v27 offset1:66
	s_and_b64 vcc, exec, s[4:5]
	v_add_u32_e32 v26, v3, v39
	s_cbranch_vccnz .LBB0_148
	v_mov_b32_e32 v27, v212
	v_mov_b32_e32 v28, v213
	v_mov_b32_e32 v24, v214
	v_mov_b32_e32 v25, v215
	s_waitcnt vmcnt(3)
	v_mul_f32_e32 v27, v64, v27
	s_waitcnt vmcnt(2)
	v_mul_f32_e32 v28, v65, v28
	ds_write2_b32 v26, v27, v28 offset1:66
	s_waitcnt vmcnt(0)
	v_pk_mul_f32 v[24:25], v[22:23], v[24:25]
	s_cbranch_execnz .LBB0_132

; __device__ __forceinline__ void transpose_item(const float* W, int N, bf16* WT, int K, int k0, int n0, int drow0, const float* gk, LAS float* scr, int lane) {
;     ...
;     for (int i = 0; i < 32; ++i) { const int kk = 2 * i + (lane >> 5); float v = wv[i]; if (gk) v *= gk[kk]; scr[kk * 33 + (lane & 31)] = v; }
.LBB0_132:
	s_waitcnt vmcnt(21)
	v_add_u32_e32 v22, v3, v40
	ds_write2_b32 v22, v24, v25 offset1:66
	s_and_b64 vcc, exec, s[4:5]
	v_add_u32_e32 v24, v3, v41
	s_cbranch_vccnz .LBB0_149
	v_mov_b32_e32 v25, v216
	v_mov_b32_e32 v26, v217
	v_mov_b32_e32 v22, v218
	v_mov_b32_e32 v23, v219
	s_waitcnt vmcnt(3)
	v_mul_f32_e32 v25, v62, v25
	s_waitcnt vmcnt(2)
	v_mul_f32_e32 v26, v63, v26
	ds_write2_b32 v24, v25, v26 offset1:66
	s_waitcnt vmcnt(0)
	v_pk_mul_f32 v[22:23], v[20:21], v[22:23]
	s_cbranch_execnz .LBB0_135

; __device__ __forceinline__ void transpose_item(const float* W, int N, bf16* WT, int K, int k0, int n0, int drow0, const float* gk, LAS float* scr, int lane) {
;     ...
;     for (int i = 0; i < 32; ++i) { const int kk = 2 * i + (lane >> 5); float v = wv[i]; if (gk) v *= gk[kk]; scr[kk * 33 + (lane & 31)] = v; }
.LBB0_135:
	s_waitcnt vmcnt(17)
	v_add_u32_e32 v20, v3, v42
	ds_write2_b32 v20, v22, v23 offset1:66
	s_and_b64 vcc, exec, s[4:5]
	v_add_u32_e32 v22, v3, v43
	s_cbranch_vccnz .LBB0_150
	v_mov_b32_e32 v23, v220
	v_mov_b32_e32 v24, v221
	v_mov_b32_e32 v20, v222
	v_mov_b32_e32 v21, v223
	s_waitcnt vmcnt(3)
	v_mul_f32_e32 v23, v60, v23
	s_waitcnt vmcnt(2)
	v_mul_f32_e32 v24, v61, v24
	ds_write2_b32 v22, v23, v24 offset1:66
	s_waitcnt vmcnt(0)
	v_pk_mul_f32 v[20:21], v[18:19], v[20:21]
	s_cbranch_execnz .LBB0_138

; __device__ __forceinline__ void transpose_item(const float* W, int N, bf16* WT, int K, int k0, int n0, int drow0, const float* gk, LAS float* scr, int lane) {
;     ...
;     for (int i = 0; i < 32; ++i) { const int kk = 2 * i + (lane >> 5); float v = wv[i]; if (gk) v *= gk[kk]; scr[kk * 33 + (lane & 31)] = v; }
.LBB0_138:
	s_waitcnt vmcnt(13)
	v_add_u32_e32 v18, v3, v44
	ds_write2_b32 v18, v20, v21 offset1:66
	s_and_b64 vcc, exec, s[4:5]
	v_add_u32_e32 v20, v3, v45
	s_cbranch_vccnz .LBB0_151
	v_mov_b32_e32 v21, v224
	v_mov_b32_e32 v22, v225
	v_mov_b32_e32 v18, v226
	v_mov_b32_e32 v19, v227
	s_waitcnt vmcnt(3)
	v_mul_f32_e32 v21, v55, v21
	s_waitcnt vmcnt(2)
	v_mul_f32_e32 v22, v56, v22
	ds_write2_b32 v20, v21, v22 offset1:66
	s_waitcnt vmcnt(0)
	v_pk_mul_f32 v[18:19], v[14:15], v[18:19]
	s_cbranch_execnz .LBB0_141

; __device__ __forceinline__ void transpose_item(const float* W, int N, bf16* WT, int K, int k0, int n0, int drow0, const float* gk, LAS float* scr, int lane) {
;     ...
;     for (int i = 0; i < 32; ++i) { const int kk = 2 * i + (lane >> 5); float v = wv[i]; if (gk) v *= gk[kk]; scr[kk * 33 + (lane & 31)] = v; }
.LBB0_141:
	s_waitcnt vmcnt(9)
	v_add_u32_e32 v14, v3, v46
	ds_write2_b32 v14, v18, v19 offset1:66
	s_and_b64 vcc, exec, s[4:5]
	v_add_u32_e32 v18, v3, v47
	s_cbranch_vccnz .LBB0_152
	v_mov_b32_e32 v19, v228
	v_mov_b32_e32 v20, v229
	v_mov_b32_e32 v14, v230
	v_mov_b32_e32 v15, v231
	s_waitcnt vmcnt(3)
	v_mul_f32_e32 v19, v58, v19
	s_waitcnt vmcnt(2)
	v_mul_f32_e32 v20, v59, v20
	ds_write2_b32 v18, v19, v20 offset1:66
	s_waitcnt vmcnt(0)
	v_pk_mul_f32 v[14:15], v[16:17], v[14:15]
	s_cbranch_execnz .LBB0_144

; __device__ __forceinline__ void transpose_item(const float* W, int N, bf16* WT, int K, int k0, int n0, int drow0, const float* gk, LAS float* scr, int lane) {
;     ...
;     for (int i = 0; i < 32; ++i) { const int kk = 2 * i + (lane >> 5); float v = wv[i]; if (gk) v *= gk[kk]; scr[kk * 33 + (lane & 31)] = v; }
.LBB0_144:
	s_and_b64 vcc, exec, s[4:5]
	s_waitcnt vmcnt(5)
	v_add_u32_e32 v16, 0x400, v18
	ds_write2_b32 v18, v14, v15 offset0:132 offset1:198
	s_cbranch_vccnz .LBB0_153
	v_mov_b32_e32 v17, v232
	v_mov_b32_e32 v18, v233
	v_mov_b32_e32 v14, v234
	v_mov_b32_e32 v15, v235
	s_waitcnt vmcnt(3)
	v_mul_f32_e32 v17, v9, v17
	s_waitcnt vmcnt(2)
	v_mul_f32_e32 v18, v11, v18
	ds_write2_b32 v16, v17, v18 offset0:8 offset1:74
	s_waitcnt vmcnt(0)
	v_pk_mul_f32 v[14:15], v[12:13], v[14:15]
	s_cbranch_execnz .LBB0_8
	s_branch .LBB0_7

; __device__ __forceinline__ void transpose_item(const float* W, int N, bf16* WT, int K, int k0, int n0, int drow0, const float* gk, LAS float* scr, int lane) {
;     ...
;     for (int i = 0; i < 32; ++i) wv[i] = W[(size_t)(k0 + 2 * i + (lane >> 5)) * N + n0 + (lane & 31)];
; __device__ __forceinline__ void p0_weight_item(const Args& a, int l, int r, LAS float* scr, int lane) {
;     ...
;     if (r < IT_OUT) {
;         const int kb = r / 32, nb = r % 32, k0 = 64 * kb;
;         const float* gk = (k0 < 256) ? a.in[17] + (size_t)l * 256 + k0 : (k0 < 768 ? a.in[18] + (size_t)l * 512 + (k0 - 256) : a.in[26] + (size_t)l * 256 + (k0 - 768));
;         transpose_item(a.in[27] + (size_t)l * DM * DM, DM, (bf16*)(wl + WL_WOUT), DM, k0, 32 * nb, 32 * nb, gk, scr, lane); return; }
.LBB0_1055:
	s_add_i32 s0, s35, 0xfffba000
	s_and_b32 s28, s0, 0x3e0
	v_or_b32_e32 v144, s4, v0
	s_lshl_b32 s82, s28, 2
	v_lshl_add_u64 v[50:51], v[18:19], 0, s[82:83]
	v_lshlrev_b64 v[34:35], 12, v[144:145]
	v_lshl_add_u64 v[34:35], v[50:51], 0, v[34:35]
	global_load_dword v83, v[34:35], off
	v_or_b32_e32 v34, 2, v144
	v_mov_b32_e32 v35, v145
	v_lshlrev_b64 v[34:35], 12, v[34:35]
	v_lshl_add_u64 v[34:35], v[50:51], 0, v[34:35]
	global_load_dword v84, v[34:35], off
	v_or_b32_e32 v34, 4, v144
	v_mov_b32_e32 v35, v145
	v_lshlrev_b64 v[34:35], 12, v[34:35]
	v_lshl_add_u64 v[34:35], v[50:51], 0, v[34:35]
	global_load_dword v48, v[34:35], off
	v_or_b32_e32 v34, 6, v144
	v_mov_b32_e32 v35, v145
	v_lshlrev_b64 v[34:35], 12, v[34:35]
	v_lshl_add_u64 v[34:35], v[50:51], 0, v[34:35]
	global_load_dword v49, v[34:35], off
	v_or_b32_e32 v34, 8, v144
	v_mov_b32_e32 v35, v145
	v_lshlrev_b64 v[34:35], 12, v[34:35]
	v_lshl_add_u64 v[34:35], v[50:51], 0, v[34:35]
	global_load_dword v81, v[34:35], off
	v_or_b32_e32 v34, 10, v144
	v_mov_b32_e32 v35, v145
	v_lshlrev_b64 v[34:35], 12, v[34:35]
	v_lshl_add_u64 v[34:35], v[50:51], 0, v[34:35]
	global_load_dword v82, v[34:35], off
	v_or_b32_e32 v34, 12, v144
	v_mov_b32_e32 v35, v145
	v_lshlrev_b64 v[34:35], 12, v[34:35]
	v_lshl_add_u64 v[34:35], v[50:51], 0, v[34:35]
	global_load_dword v46, v[34:35], off
	v_or_b32_e32 v34, 14, v144
	v_mov_b32_e32 v35, v145
	v_lshlrev_b64 v[34:35], 12, v[34:35]
	v_lshl_add_u64 v[34:35], v[50:51], 0, v[34:35]
	global_load_dword v47, v[34:35], off
	v_or_b32_e32 v34, 16, v144
	v_mov_b32_e32 v35, v145
	v_lshlrev_b64 v[34:35], 12, v[34:35]
	v_lshl_add_u64 v[34:35], v[50:51], 0, v[34:35]
	global_load_dword v79, v[34:35], off
	v_or_b32_e32 v34, 18, v144
	v_mov_b32_e32 v35, v145
	v_lshlrev_b64 v[34:35], 12, v[34:35]
	v_lshl_add_u64 v[34:35], v[50:51], 0, v[34:35]
	global_load_dword v80, v[34:35], off
	v_or_b32_e32 v34, 20, v144
	v_mov_b32_e32 v35, v145
	v_lshlrev_b64 v[34:35], 12, v[34:35]
	v_lshl_add_u64 v[34:35], v[50:51], 0, v[34:35]
	global_load_dword v44, v[34:35], off
	v_or_b32_e32 v34, 22, v144
	v_mov_b32_e32 v35, v145
	v_lshlrev_b64 v[34:35], 12, v[34:35]
	v_lshl_add_u64 v[34:35], v[50:51], 0, v[34:35]
	global_load_dword v45, v[34:35], off
	v_or_b32_e32 v34, 24, v144
	v_mov_b32_e32 v35, v145
	v_lshlrev_b64 v[34:35], 12, v[34:35]
	v_lshl_add_u64 v[34:35], v[50:51], 0, v[34:35]
	global_load_dword v77, v[34:35], off
	v_or_b32_e32 v34, 26, v144
	v_mov_b32_e32 v35, v145
	v_lshlrev_b64 v[34:35], 12, v[34:35]
	v_lshl_add_u64 v[34:35], v[50:51], 0, v[34:35]
	global_load_dword v78, v[34:35], off
	v_or_b32_e32 v34, 28, v144
	v_mov_b32_e32 v35, v145
	v_lshlrev_b64 v[34:35], 12, v[34:35]
	v_lshl_add_u64 v[34:35], v[50:51], 0, v[34:35]
	global_load_dword v42, v[34:35], off
	v_or_b32_e32 v34, 30, v144
	v_mov_b32_e32 v35, v145
	v_lshlrev_b64 v[34:35], 12, v[34:35]
	v_lshl_add_u64 v[34:35], v[50:51], 0, v[34:35]
	global_load_dword v43, v[34:35], off
	v_or_b32_e32 v34, 32, v144
	v_mov_b32_e32 v35, v145
	v_lshlrev_b64 v[34:35], 12, v[34:35]
	v_lshl_add_u64 v[34:35], v[50:51], 0, v[34:35]
	global_load_dword v75, v[34:35], off
	v_or_b32_e32 v34, 34, v144
	v_mov_b32_e32 v35, v145
	v_lshlrev_b64 v[34:35], 12, v[34:35]
	v_lshl_add_u64 v[34:35], v[50:51], 0, v[34:35]
	global_load_dword v76, v[34:35], off
	v_or_b32_e32 v34, 36, v144
	v_mov_b32_e32 v35, v145
	v_lshlrev_b64 v[34:35], 12, v[34:35]
	v_lshl_add_u64 v[34:35], v[50:51], 0, v[34:35]
	global_load_dword v40, v[34:35], off
	v_or_b32_e32 v34, 38, v144
	v_mov_b32_e32 v35, v145
	v_lshlrev_b64 v[34:35], 12, v[34:35]
	v_lshl_add_u64 v[34:35], v[50:51], 0, v[34:35]
	global_load_dword v41, v[34:35], off
	v_or_b32_e32 v34, 40, v144
	v_mov_b32_e32 v35, v145
	v_lshlrev_b64 v[34:35], 12, v[34:35]
	v_lshl_add_u64 v[34:35], v[50:51], 0, v[34:35]
	global_load_dword v73, v[34:35], off
	v_or_b32_e32 v34, 42, v144
	v_mov_b32_e32 v35, v145
	v_lshlrev_b64 v[34:35], 12, v[34:35]
	v_lshl_add_u64 v[34:35], v[50:51], 0, v[34:35]
	global_load_dword v74, v[34:35], off
	v_or_b32_e32 v34, 44, v144
	v_mov_b32_e32 v35, v145
	v_lshlrev_b64 v[34:35], 12, v[34:35]
	v_lshl_add_u64 v[34:35], v[50:51], 0, v[34:35]
	global_load_dword v38, v[34:35], off
	v_or_b32_e32 v34, 46, v144
	v_mov_b32_e32 v35, v145
	v_lshlrev_b64 v[34:35], 12, v[34:35]
	v_lshl_add_u64 v[34:35], v[50:51], 0, v[34:35]
	global_load_dword v39, v[34:35], off
	v_or_b32_e32 v34, 48, v144
	v_mov_b32_e32 v35, v145
	v_lshlrev_b64 v[34:35], 12, v[34:35]
	v_lshl_add_u64 v[34:35], v[50:51], 0, v[34:35]
	global_load_dword v71, v[34:35], off
	v_or_b32_e32 v34, 50, v144
	v_mov_b32_e32 v35, v145
	v_lshlrev_b64 v[34:35], 12, v[34:35]
	v_lshl_add_u64 v[34:35], v[50:51], 0, v[34:35]
	global_load_dword v72, v[34:35], off
	v_or_b32_e32 v34, 52, v144
	v_mov_b32_e32 v35, v145
	v_lshlrev_b64 v[34:35], 12, v[34:35]
	v_lshl_add_u64 v[34:35], v[50:51], 0, v[34:35]
	global_load_dword v36, v[34:35], off
	v_or_b32_e32 v34, 54, v144
	v_mov_b32_e32 v35, v145
	v_lshlrev_b64 v[34:35], 12, v[34:35]
	v_lshl_add_u64 v[34:35], v[50:51], 0, v[34:35]
	global_load_dword v37, v[34:35], off
	v_or_b32_e32 v34, 56, v144
	v_mov_b32_e32 v35, v145
	v_lshlrev_b64 v[34:35], 12, v[34:35]
	v_lshl_add_u64 v[34:35], v[50:51], 0, v[34:35]
	global_load_dword v69, v[34:35], off
	v_or_b32_e32 v34, 58, v144
	v_mov_b32_e32 v35, v145
	v_lshlrev_b64 v[34:35], 12, v[34:35]
	v_lshl_add_u64 v[34:35], v[50:51], 0, v[34:35]
	global_load_dword v70, v[34:35], off
	v_or_b32_e32 v34, 60, v144
	v_mov_b32_e32 v35, v145
	v_or_b32_e32 v144, 62, v144
	v_lshlrev_b64 v[34:35], 12, v[34:35]
	v_lshlrev_b64 v[86:87], 12, v[144:145]
	v_lshl_add_u64 v[34:35], v[50:51], 0, v[34:35]
	v_lshl_add_u64 v[50:51], v[50:51], 0, v[86:87]
	global_load_dword v34, v[34:35], off
	s_cmp_lg_u64 s[6:7], 0
	global_load_dword v35, v[50:51], off
	s_cselect_b64 s[0:1], -1, 0
	s_cmp_eq_u64 s[6:7], 0
	s_cbranch_scc1 .LBB0_1191
; __device__ __forceinline__ void transpose_item(const float* W, int N, bf16* WT, int K, int k0, int n0, int drow0, const float* gk, LAS float* scr, int lane) {
;     ...
;     for (int i = 0; i < 32; ++i) { const int kk = 2 * i + (lane >> 5); float v = wv[i]; if (gk) v *= gk[kk]; scr[kk * 33 + (lane & 31)] = v; }
	v_lshlrev_b32_e32 v51, 2, v0
	s_waitcnt vmcnt(32)
	global_load_dword v204, v51, s[6:7]
	global_load_dword v205, v51, s[6:7] offset:8
	global_load_dword v206, v51, s[6:7] offset:16
	global_load_dword v207, v51, s[6:7] offset:24
	global_load_dword v208, v51, s[6:7] offset:32
	global_load_dword v209, v51, s[6:7] offset:40
	global_load_dword v210, v51, s[6:7] offset:48
	global_load_dword v211, v51, s[6:7] offset:56
	global_load_dword v212, v51, s[6:7] offset:64
	global_load_dword v213, v51, s[6:7] offset:72
	global_load_dword v214, v51, s[6:7] offset:80
	global_load_dword v215, v51, s[6:7] offset:88
	global_load_dword v216, v51, s[6:7] offset:96
	global_load_dword v217, v51, s[6:7] offset:104
	global_load_dword v218, v51, s[6:7] offset:112
	global_load_dword v219, v51, s[6:7] offset:120
	global_load_dword v220, v51, s[6:7] offset:128
	global_load_dword v221, v51, s[6:7] offset:136
	global_load_dword v222, v51, s[6:7] offset:144
	global_load_dword v223, v51, s[6:7] offset:152
	global_load_dword v224, v51, s[6:7] offset:160
	global_load_dword v225, v51, s[6:7] offset:168
	global_load_dword v226, v51, s[6:7] offset:176
	global_load_dword v227, v51, s[6:7] offset:184
	global_load_dword v228, v51, s[6:7] offset:192
	global_load_dword v229, v51, s[6:7] offset:200
	global_load_dword v230, v51, s[6:7] offset:208
	global_load_dword v231, v51, s[6:7] offset:216
	global_load_dword v232, v51, s[6:7] offset:224
	global_load_dword v233, v51, s[6:7] offset:232
	global_load_dword v234, v51, s[6:7] offset:240
	s_waitcnt vmcnt(62)
	global_load_dword v235, v51, s[6:7] offset:248
	s_waitcnt vmcnt(0)
	v_mov_b32_e32 v50, v204
	v_mov_b32_e32 v85, v205
	s_waitcnt vmcnt(0)
	v_mul_f32_e32 v50, v83, v50
	v_mul_f32_e32 v85, v84, v85
	ds_write_b32 v3, v50
	v_add_u32_e32 v50, v1, v56
	ds_write_b32 v50, v85
	v_mov_b32_e32 v50, v206
	s_nop 0
	v_mov_b32_e32 v51, v207
	s_waitcnt vmcnt(0)
	v_pk_mul_f32 v[50:51], v[48:49], v[50:51]
	s_cbranch_execnz .LBB0_1058

; __device__ __forceinline__ void transpose_item(const float* W, int N, bf16* WT, int K, int k0, int n0, int drow0, const float* gk, LAS float* scr, int lane) {
;     ...
;     for (int i = 0; i < 32; ++i) { const int kk = 2 * i + (lane >> 5); float v = wv[i]; if (gk) v *= gk[kk]; scr[kk * 33 + (lane & 31)] = v; }
.LBB0_1058:
	s_waitcnt vmcnt(0)
	v_add_u32_e32 v48, v1, v57
	ds_write2_b32 v48, v50, v51 offset1:66
	v_cndmask_b32_e64 v48, 0, 1, s[0:1]
	v_cmp_ne_u32_e64 s[36:37], 1, v48
	s_andn2_b64 vcc, exec, s[0:1]
	s_cbranch_vccnz .LBB0_1192
	v_lshlrev_b32_e32 v49, 2, v0
	v_mov_b32_e32 v48, v208
	v_mov_b32_e32 v50, v209
	v_add_u32_e32 v51, v1, v58
	s_waitcnt vmcnt(1)
	v_mul_f32_e32 v48, v81, v48
	s_waitcnt vmcnt(0)
	v_mul_f32_e32 v50, v82, v50
	ds_write2_b32 v51, v48, v50 offset1:66
	v_mov_b32_e32 v48, v210
	s_nop 0
	v_mov_b32_e32 v49, v211
	s_waitcnt vmcnt(0)
	v_pk_mul_f32 v[48:49], v[46:47], v[48:49]
	s_cbranch_execnz .LBB0_1061

; __device__ __forceinline__ void transpose_item(const float* W, int N, bf16* WT, int K, int k0, int n0, int drow0, const float* gk, LAS float* scr, int lane) {
;     ...
;     for (int i = 0; i < 32; ++i) { const int kk = 2 * i + (lane >> 5); float v = wv[i]; if (gk) v *= gk[kk]; scr[kk * 33 + (lane & 31)] = v; }
.LBB0_1061:
	v_add_u32_e32 v46, v1, v59
	s_and_b64 vcc, exec, s[36:37]
	ds_write2_b32 v46, v48, v49 offset1:66
	s_cbranch_vccnz .LBB0_1193
	v_lshlrev_b32_e32 v47, 2, v0
	v_mov_b32_e32 v46, v212
	v_mov_b32_e32 v48, v213
	v_add_u32_e32 v49, v1, v60
	s_waitcnt vmcnt(1)
	v_mul_f32_e32 v46, v79, v46
	s_waitcnt vmcnt(0)
	v_mul_f32_e32 v48, v80, v48
	ds_write2_b32 v49, v46, v48 offset1:66
	v_mov_b32_e32 v46, v214
	s_nop 0
	v_mov_b32_e32 v47, v215
	s_waitcnt vmcnt(0)
	v_pk_mul_f32 v[46:47], v[44:45], v[46:47]
	s_cbranch_execnz .LBB0_1064

; __device__ __forceinline__ void transpose_item(const float* W, int N, bf16* WT, int K, int k0, int n0, int drow0, const float* gk, LAS float* scr, int lane) {
;     ...
;     for (int i = 0; i < 32; ++i) { const int kk = 2 * i + (lane >> 5); float v = wv[i]; if (gk) v *= gk[kk]; scr[kk * 33 + (lane & 31)] = v; }
.LBB0_1064:
	v_add_u32_e32 v44, v1, v61
	s_and_b64 vcc, exec, s[36:37]
	ds_write2_b32 v44, v46, v47 offset1:66
	s_cbranch_vccnz .LBB0_1194
	v_lshlrev_b32_e32 v45, 2, v0
	v_mov_b32_e32 v44, v216
	v_mov_b32_e32 v46, v217
	v_add_u32_e32 v47, v1, v62
	s_waitcnt vmcnt(1)
	v_mul_f32_e32 v44, v77, v44
	s_waitcnt vmcnt(0)
	v_mul_f32_e32 v46, v78, v46
	ds_write2_b32 v47, v44, v46 offset1:66
	v_mov_b32_e32 v44, v218
	s_nop 0
	v_mov_b32_e32 v45, v219
	s_waitcnt vmcnt(0)
	v_pk_mul_f32 v[44:45], v[42:43], v[44:45]
	s_cbranch_execnz .LBB0_1067

; __device__ __forceinline__ void transpose_item(const float* W, int N, bf16* WT, int K, int k0, int n0, int drow0, const float* gk, LAS float* scr, int lane) {
;     ...
;     for (int i = 0; i < 32; ++i) { const int kk = 2 * i + (lane >> 5); float v = wv[i]; if (gk) v *= gk[kk]; scr[kk * 33 + (lane & 31)] = v; }
.LBB0_1067:
	v_add_u32_e32 v42, v1, v63
	s_and_b64 vcc, exec, s[36:37]
	ds_write2_b32 v42, v44, v45 offset1:66
	s_cbranch_vccnz .LBB0_1195
	v_lshlrev_b32_e32 v43, 2, v0
	v_mov_b32_e32 v42, v220
	v_mov_b32_e32 v44, v221
	v_add_u32_e32 v45, v1, v64
	s_waitcnt vmcnt(1)
	v_mul_f32_e32 v42, v75, v42
	s_waitcnt vmcnt(0)
	v_mul_f32_e32 v44, v76, v44
	ds_write2_b32 v45, v42, v44 offset1:66
	v_mov_b32_e32 v42, v222
	s_nop 0
	v_mov_b32_e32 v43, v223
	s_waitcnt vmcnt(0)
	v_pk_mul_f32 v[42:43], v[40:41], v[42:43]
	s_cbranch_execnz .LBB0_1070

; __device__ __forceinline__ void transpose_item(const float* W, int N, bf16* WT, int K, int k0, int n0, int drow0, const float* gk, LAS float* scr, int lane) {
;     ...
;     for (int i = 0; i < 32; ++i) { const int kk = 2 * i + (lane >> 5); float v = wv[i]; if (gk) v *= gk[kk]; scr[kk * 33 + (lane & 31)] = v; }
.LBB0_1070:
	v_add_u32_e32 v40, v1, v65
	s_and_b64 vcc, exec, s[36:37]
	ds_write2_b32 v40, v42, v43 offset1:66
	s_cbranch_vccnz .LBB0_1196
	v_lshlrev_b32_e32 v41, 2, v0
	v_mov_b32_e32 v40, v224
	v_mov_b32_e32 v42, v225
	v_add_u32_e32 v43, v1, v66
	s_waitcnt vmcnt(1)
	v_mul_f32_e32 v40, v73, v40
	s_waitcnt vmcnt(0)
	v_mul_f32_e32 v42, v74, v42
	ds_write2_b32 v43, v40, v42 offset1:66
	v_mov_b32_e32 v40, v226
	s_nop 0
	v_mov_b32_e32 v41, v227
	s_waitcnt vmcnt(0)
	v_pk_mul_f32 v[40:41], v[38:39], v[40:41]
	s_cbranch_execnz .LBB0_1073

; __device__ __forceinline__ void transpose_item(const float* W, int N, bf16* WT, int K, int k0, int n0, int drow0, const float* gk, LAS float* scr, int lane) {
;     ...
;     for (int i = 0; i < 32; ++i) { const int kk = 2 * i + (lane >> 5); float v = wv[i]; if (gk) v *= gk[kk]; scr[kk * 33 + (lane & 31)] = v; }
.LBB0_1073:
	v_add_u32_e32 v38, v1, v67
	s_and_b64 vcc, exec, s[36:37]
	ds_write2_b32 v38, v40, v41 offset1:66
	s_cbranch_vccnz .LBB0_1197
	v_lshlrev_b32_e32 v39, 2, v0
	v_mov_b32_e32 v38, v228
	v_mov_b32_e32 v40, v229
	v_add_u32_e32 v41, v1, v68
	s_waitcnt vmcnt(1)
	v_mul_f32_e32 v38, v71, v38
	s_waitcnt vmcnt(0)
	v_mul_f32_e32 v40, v72, v40
	ds_write2_b32 v41, v38, v40 offset1:66
	v_mov_b32_e32 v38, v230
	s_nop 0
	v_mov_b32_e32 v39, v231
	s_waitcnt vmcnt(0)
	v_pk_mul_f32 v[38:39], v[36:37], v[38:39]
	s_cbranch_execnz .LBB0_1076

; __device__ __forceinline__ void transpose_item(const float* W, int N, bf16* WT, int K, int k0, int n0, int drow0, const float* gk, LAS float* scr, int lane) {
;     ...
;     for (int i = 0; i < 32; ++i) { const int kk = 2 * i + (lane >> 5); float v = wv[i]; if (gk) v *= gk[kk]; scr[kk * 33 + (lane & 31)] = v; }
.LBB0_1076:
	v_add_u32_e32 v36, v1, v68
	ds_write2_b32 v36, v38, v39 offset0:132 offset1:198
	s_and_b64 vcc, exec, s[36:37]
	v_add_u32_e32 v38, 0x400, v36
	s_cbranch_vccnz .LBB0_1198
	v_lshlrev_b32_e32 v37, 2, v0
	v_mov_b32_e32 v36, v232
	v_mov_b32_e32 v39, v233
	s_waitcnt vmcnt(1)
	v_mul_f32_e32 v36, v69, v36
	s_waitcnt vmcnt(0)
	v_mul_f32_e32 v39, v70, v39
	ds_write2_b32 v38, v36, v39 offset0:8 offset1:74
	v_mov_b32_e32 v36, v234
	s_nop 0
	v_mov_b32_e32 v37, v235
	s_waitcnt vmcnt(0)
	v_pk_mul_f32 v[36:37], v[34:35], v[36:37]
	s_cbranch_execnz .LBB0_1079

; __device__ __forceinline__ void transpose_item(const float* W, int N, bf16* WT, int K, int k0, int n0, int drow0, const float* gk, LAS float* scr, int lane) {
;     ...
;     for (int i = 0; i < 32; ++i) wv[i] = W[(size_t)(k0 + 2 * i + (lane >> 5)) * N + n0 + (lane & 31)];
; __device__ __forceinline__ void p0_weight_item(const Args& a, int l, int r, LAS float* scr, int lane) {
;     ...
;     if (r < IT_BIG) {
;         const int kb = r / 88, nb = r % 88, k0 = 64 * kb, n0 = 32 * nb; const int tile = n0 >> 8, c0 = n0 & 255;
;         int drow = n0;
;         if (tile >= 1 && tile <= 4) { const int hh = c0 >> 7, d0 = c0 & 127, bj = d0 >> 6, dd0 = d0 & 63; drow = tile * 256 + bj * 128 + hh * 64 + dd0; }
;         transpose_item(a.in[6] + (size_t)l * DM * IW, IW, (bf16*)(wl + WL_WIN), DM, k0, n0, drow, a.in[5] + (size_t)l * DM + k0, scr, lane); return; }
.LBB0_1084:
	s_lshl_b32 s1, s1, 6
	s_and_b32 s7, s1, 0xffc0
	s_lshl_b32 s1, s7, 2
	v_readlane_b32 s4, v254, 19
	s_add_u32 s4, s4, s1
	v_readlane_b32 s1, v254, 20
	s_addc_u32 s5, s1, 0
	v_or_b32_e32 v36, s7, v0
	s_lshl_b32 s82, s0, 2
	v_lshl_add_u64 v[34:35], v[22:23], 0, s[82:83]
	v_mul_u32_u24_e32 v144, 0x2c00, v36
	v_lshl_add_u64 v[50:51], v[34:35], 0, v[144:145]
	s_movk_i32 s0, 0x5000
	v_add_co_u32_e32 v34, vcc, s0, v50
	s_mov_b32 s0, 0xb000
	s_nop 0
	v_addc_co_u32_e32 v35, vcc, 0, v51, vcc
	global_load_dword v84, v[34:35], off offset:2048
	v_add_co_u32_e32 v34, vcc, s0, v50
	s_mov_b32 s0, 0x10000
	s_nop 0
	v_addc_co_u32_e32 v35, vcc, 0, v51, vcc
	global_load_dword v83, v[50:51], off
	global_load_dword v48, v[34:35], off
	v_add_co_u32_e32 v34, vcc, s0, v50
	s_mov_b32 s0, 0x16000
	s_nop 0
	v_addc_co_u32_e32 v35, vcc, 0, v51, vcc
	global_load_dword v49, v[34:35], off offset:2048
	v_add_co_u32_e32 v34, vcc, s0, v50
	s_mov_b32 s0, 0x1b000
	s_nop 0
	v_addc_co_u32_e32 v35, vcc, 0, v51, vcc
	global_load_dword v81, v[34:35], off
	v_add_co_u32_e32 v34, vcc, s0, v50
	s_mov_b32 s0, 0x21000
	s_nop 0
	v_addc_co_u32_e32 v35, vcc, 0, v51, vcc
	global_load_dword v82, v[34:35], off offset:2048
	v_add_co_u32_e32 v34, vcc, s0, v50
	s_mov_b32 s0, 0x26000
	s_nop 0
	v_addc_co_u32_e32 v35, vcc, 0, v51, vcc
	global_load_dword v46, v[34:35], off
	v_add_co_u32_e32 v34, vcc, s0, v50
	s_mov_b32 s0, 0x2c000
	s_nop 0
	v_addc_co_u32_e32 v35, vcc, 0, v51, vcc
	global_load_dword v47, v[34:35], off offset:2048
	v_add_co_u32_e32 v34, vcc, s0, v50
	s_mov_b32 s0, 0x31000
	s_nop 0
	v_addc_co_u32_e32 v35, vcc, 0, v51, vcc
	global_load_dword v79, v[34:35], off
	v_add_co_u32_e32 v34, vcc, s0, v50
	s_mov_b32 s0, 0x37000
	s_nop 0
	v_addc_co_u32_e32 v35, vcc, 0, v51, vcc
	global_load_dword v80, v[34:35], off offset:2048
	v_add_co_u32_e32 v34, vcc, s0, v50
	s_mov_b32 s0, 0x3c000
	s_nop 0
	v_addc_co_u32_e32 v35, vcc, 0, v51, vcc
	global_load_dword v44, v[34:35], off
	v_add_co_u32_e32 v34, vcc, s0, v50
	s_mov_b32 s0, 0x42000
	s_nop 0
	v_addc_co_u32_e32 v35, vcc, 0, v51, vcc
	global_load_dword v45, v[34:35], off offset:2048
	v_add_co_u32_e32 v34, vcc, s0, v50
	s_mov_b32 s0, 0x47000
	s_nop 0
	v_addc_co_u32_e32 v35, vcc, 0, v51, vcc
	global_load_dword v77, v[34:35], off
	v_add_co_u32_e32 v34, vcc, s0, v50
	s_mov_b32 s0, 0x4d000
	s_nop 0
	v_addc_co_u32_e32 v35, vcc, 0, v51, vcc
	global_load_dword v78, v[34:35], off offset:2048
	v_add_co_u32_e32 v34, vcc, s0, v50
	s_mov_b32 s0, 0x52000
	s_nop 0
	v_addc_co_u32_e32 v35, vcc, 0, v51, vcc
	global_load_dword v42, v[34:35], off
	v_add_co_u32_e32 v34, vcc, s0, v50
	s_mov_b32 s0, 0x58000
	s_nop 0
	v_addc_co_u32_e32 v35, vcc, 0, v51, vcc
	global_load_dword v43, v[34:35], off offset:2048
	v_add_co_u32_e32 v34, vcc, s0, v50
	s_mov_b32 s0, 0x5d000
	s_nop 0
	v_addc_co_u32_e32 v35, vcc, 0, v51, vcc
	global_load_dword v75, v[34:35], off
	v_add_co_u32_e32 v34, vcc, s0, v50
	s_mov_b32 s0, 0x63000
	s_nop 0
	v_addc_co_u32_e32 v35, vcc, 0, v51, vcc
	global_load_dword v76, v[34:35], off offset:2048
	v_add_co_u32_e32 v34, vcc, s0, v50
	s_mov_b32 s0, 0x68000
	s_nop 0
	v_addc_co_u32_e32 v35, vcc, 0, v51, vcc
	global_load_dword v40, v[34:35], off
	v_add_co_u32_e32 v34, vcc, s0, v50
	s_mov_b32 s0, 0x6e000
	s_nop 0
	v_addc_co_u32_e32 v35, vcc, 0, v51, vcc
	global_load_dword v41, v[34:35], off offset:2048
	v_add_co_u32_e32 v34, vcc, s0, v50
	s_mov_b32 s0, 0x73000
	s_nop 0
	v_addc_co_u32_e32 v35, vcc, 0, v51, vcc
	global_load_dword v73, v[34:35], off
	v_add_co_u32_e32 v34, vcc, s0, v50
	s_mov_b32 s0, 0x79000
	s_nop 0
	v_addc_co_u32_e32 v35, vcc, 0, v51, vcc
	global_load_dword v74, v[34:35], off offset:2048
	v_add_co_u32_e32 v34, vcc, s0, v50
	s_mov_b32 s0, 0x7e000
	s_nop 0
	v_addc_co_u32_e32 v35, vcc, 0, v51, vcc
	global_load_dword v38, v[34:35], off
	v_add_co_u32_e32 v34, vcc, s0, v50
	s_mov_b32 s0, 0x84000
	s_nop 0
	v_addc_co_u32_e32 v35, vcc, 0, v51, vcc
	global_load_dword v39, v[34:35], off offset:2048
	v_add_co_u32_e32 v34, vcc, s0, v50
	s_mov_b32 s0, 0x89000
	s_nop 0
	v_addc_co_u32_e32 v35, vcc, 0, v51, vcc
	global_load_dword v71, v[34:35], off
	v_add_co_u32_e32 v34, vcc, s0, v50
	s_mov_b32 s0, 0x8f000
	s_nop 0
	v_addc_co_u32_e32 v35, vcc, 0, v51, vcc
	global_load_dword v72, v[34:35], off offset:2048
	v_add_co_u32_e32 v34, vcc, s0, v50
	s_mov_b32 s0, 0x94000
	s_nop 0
	v_addc_co_u32_e32 v35, vcc, 0, v51, vcc
	global_load_dword v36, v[34:35], off
	v_add_co_u32_e32 v34, vcc, s0, v50
	s_mov_b32 s0, 0x9a000
	s_nop 0
	v_addc_co_u32_e32 v35, vcc, 0, v51, vcc
	global_load_dword v37, v[34:35], off offset:2048
	v_add_co_u32_e32 v34, vcc, s0, v50
	v_readlane_b32 s0, v251, 38
	s_nop 0
	v_addc_co_u32_e32 v35, vcc, 0, v51, vcc
	global_load_dword v69, v[34:35], off
	v_add_co_u32_e32 v34, vcc, 0x9f000, v50
	v_readlane_b32 s1, v251, 39
	s_nop 0
	v_addc_co_u32_e32 v35, vcc, 0, v51, vcc
	global_load_dword v70, v[34:35], off offset:2048
	v_add_co_u32_e32 v34, vcc, 0xa5000, v50
	s_nop 1
	v_addc_co_u32_e32 v35, vcc, 0, v51, vcc
	v_add_co_u32_e32 v50, vcc, 0xaa000, v50
	global_load_dword v34, v[34:35], off
	s_nop 0
	v_addc_co_u32_e32 v51, vcc, 0, v51, vcc
	global_load_dword v35, v[50:51], off offset:2048
	v_cndmask_b32_e64 v50, 0, 1, s[0:1]
	v_cmp_ne_u32_e64 s[36:37], 1, v50
	s_andn2_b64 vcc, exec, s[0:1]
	s_cbranch_vccnz .LBB0_1183
; __device__ __forceinline__ void transpose_item(const float* W, int N, bf16* WT, int K, int k0, int n0, int drow0, const float* gk, LAS float* scr, int lane) {
;     ...
;     for (int i = 0; i < 32; ++i) { const int kk = 2 * i + (lane >> 5); float v = wv[i]; if (gk) v *= gk[kk]; scr[kk * 33 + (lane & 31)] = v; }
	v_lshlrev_b32_e32 v51, 2, v0
	s_waitcnt vmcnt(32)
	global_load_dword v204, v51, s[4:5]
	global_load_dword v205, v51, s[4:5] offset:8
	global_load_dword v206, v51, s[4:5] offset:16
	global_load_dword v207, v51, s[4:5] offset:24
	global_load_dword v208, v51, s[4:5] offset:32
	global_load_dword v209, v51, s[4:5] offset:40
	global_load_dword v210, v51, s[4:5] offset:48
	global_load_dword v211, v51, s[4:5] offset:56
	global_load_dword v212, v51, s[4:5] offset:64
	global_load_dword v213, v51, s[4:5] offset:72
	global_load_dword v214, v51, s[4:5] offset:80
	global_load_dword v215, v51, s[4:5] offset:88
	global_load_dword v216, v51, s[4:5] offset:96
	global_load_dword v217, v51, s[4:5] offset:104
	global_load_dword v218, v51, s[4:5] offset:112
	global_load_dword v219, v51, s[4:5] offset:120
	global_load_dword v220, v51, s[4:5] offset:128
	global_load_dword v221, v51, s[4:5] offset:136
	global_load_dword v222, v51, s[4:5] offset:144
	global_load_dword v223, v51, s[4:5] offset:152
	global_load_dword v224, v51, s[4:5] offset:160
	global_load_dword v225, v51, s[4:5] offset:168
	global_load_dword v226, v51, s[4:5] offset:176
	global_load_dword v227, v51, s[4:5] offset:184
	global_load_dword v228, v51, s[4:5] offset:192
	global_load_dword v229, v51, s[4:5] offset:200
	global_load_dword v230, v51, s[4:5] offset:208
	global_load_dword v231, v51, s[4:5] offset:216
	global_load_dword v232, v51, s[4:5] offset:224
	global_load_dword v233, v51, s[4:5] offset:232
	global_load_dword v234, v51, s[4:5] offset:240
	s_waitcnt vmcnt(62)
	global_load_dword v235, v51, s[4:5] offset:248
	s_waitcnt vmcnt(0)
	v_mov_b32_e32 v50, v204
	v_mov_b32_e32 v85, v205
	s_waitcnt vmcnt(0)
	v_mul_f32_e32 v50, v83, v50
	v_mul_f32_e32 v85, v84, v85
	ds_write_b32 v3, v50
	v_add_u32_e32 v50, v1, v56
	ds_write_b32 v50, v85
	v_mov_b32_e32 v50, v206
	s_nop 0
	v_mov_b32_e32 v51, v207
	s_waitcnt vmcnt(0)
	v_pk_mul_f32 v[50:51], v[48:49], v[50:51]
	s_cbranch_execnz .LBB0_1087

; __device__ __forceinline__ void transpose_item(const float* W, int N, bf16* WT, int K, int k0, int n0, int drow0, const float* gk, LAS float* scr, int lane) {
;     ...
;     for (int i = 0; i < 32; ++i) { const int kk = 2 * i + (lane >> 5); float v = wv[i]; if (gk) v *= gk[kk]; scr[kk * 33 + (lane & 31)] = v; }
.LBB0_1087:
	s_waitcnt vmcnt(0)
	v_add_u32_e32 v48, v1, v57
	s_and_b64 vcc, exec, s[36:37]
	ds_write2_b32 v48, v50, v51 offset1:66
	s_cbranch_vccnz .LBB0_1184
	v_lshlrev_b32_e32 v49, 2, v0
	v_mov_b32_e32 v48, v208
	v_mov_b32_e32 v50, v209
	v_add_u32_e32 v51, v1, v58
	s_waitcnt vmcnt(1)
	v_mul_f32_e32 v48, v81, v48
	s_waitcnt vmcnt(0)
	v_mul_f32_e32 v50, v82, v50
	ds_write2_b32 v51, v48, v50 offset1:66
	v_mov_b32_e32 v48, v210
	s_nop 0
	v_mov_b32_e32 v49, v211
	s_waitcnt vmcnt(0)
	v_pk_mul_f32 v[48:49], v[46:47], v[48:49]
	s_cbranch_execnz .LBB0_1090

; __device__ __forceinline__ void transpose_item(const float* W, int N, bf16* WT, int K, int k0, int n0, int drow0, const float* gk, LAS float* scr, int lane) {
;     ...
;     for (int i = 0; i < 32; ++i) wv[i] = W[(size_t)(k0 + 2 * i + (lane >> 5)) * N + n0 + (lane & 31)];
; __device__ __forceinline__ void p0_weight_item(const Args& a, int l, int r, LAS float* scr, int lane) {
;     ...
;         if (r < 2 * IT_BIG) { const int up = r >= IT_BIG; const int it = r - up * IT_BIG; const int kb = it / 88, nb = it % 88, k0 = 64 * kb, n0 = 32 * nb;
;             const float* W = a.in[(f ? 29 : 2) + up] + (size_t)l * DM * FF;
;             transpose_item(W, FF, gu, DM, k0, n0, (n0 >> 7) * 256 + up * 128 + (n0 & 127), nrm + k0, scr, lane); return; }
.LBB0_1113:
	s_andn2_b64 vcc, exec, s[0:1]
	s_cbranch_vccnz .LBB0_1139
	s_cmpk_gt_u32 s39, 0x15ff
	v_readlane_b32 s40, v250, 59
	s_cselect_b64 s[4:5], -1, 0
	v_readlane_b32 s41, v250, 60
	v_readlane_b32 s42, v250, 61
	v_readlane_b32 s43, v250, 62
	v_readlane_b32 s44, v250, 63
	v_readlane_b32 s45, v251, 0
	v_readlane_b32 s46, v251, 1
	v_readlane_b32 s47, v251, 2
	v_readlane_b32 s48, v251, 3
	v_readlane_b32 s49, v251, 4
	v_readlane_b32 s50, v251, 5
	v_readlane_b32 s51, v251, 6
	s_and_b64 s[0:1], s[4:5], exec
	v_readlane_b32 s52, v251, 7
	v_readlane_b32 s53, v251, 8
	v_readlane_b32 s54, v251, 9
	v_readlane_b32 s55, v251, 10
	s_mov_b64 s[40:41], s[44:45]
	s_cselect_b32 s0, 0xfa80, 0
	s_mov_b64 s[42:43], s[46:47]
	s_mov_b64 s[44:45], s[48:49]
	s_mov_b64 s[46:47], s[50:51]
	s_mov_b64 s[48:49], s[52:53]
	s_cselect_b32 s1, s49, s47
	s_cselect_b32 s7, s48, s46
	s_add_i32 s0, s0, s27
	s_addk_i32 s0, 0x1080
	s_sext_i32_i16 s6, s0
	s_mulk_i32 s6, 0xba3
	s_lshr_b32 s24, s6, 31
	s_ashr_i32 s6, s6, 18
	s_add_i32 s6, s6, s24
	s_mul_i32 s24, s6, 0x58
	s_sub_i32 s0, s0, s24
	s_sext_i32_i16 s24, s0
	s_lshl_b32 s28, s6, 6
	s_lshl_b32 s6, s24, 5
	s_add_u32 s25, s7, s81
	s_addc_u32 s36, s1, s80
	s_ashr_i32 s29, s28, 31
	s_lshl_b64 s[0:1], s[28:29], 2
	v_readlane_b32 s7, v254, 27
	s_add_u32 s30, s7, s0
	v_readlane_b32 s0, v254, 28
	s_addc_u32 s31, s0, s1
	s_ashr_i32 s7, s6, 31
	s_lshl_b64 s[0:1], s[6:7], 2
	v_or_b32_e32 v36, s28, v0
	s_add_u32 s0, s25, s0
	s_addc_u32 s1, s36, s1
	v_lshlrev_b32_e32 v144, 2, v2
	v_mul_i32_i24_e32 v36, 0x2c00, v36
	v_lshl_add_u64 v[34:35], s[0:1], 0, v[144:145]
	v_ashrrev_i32_e32 v37, 31, v36
	v_lshl_add_u64 v[50:51], v[34:35], 0, v[36:37]
	s_movk_i32 s0, 0x5000
	v_add_co_u32_e32 v34, vcc, s0, v50
	s_mov_b32 s0, 0xb000
	s_nop 0
	v_addc_co_u32_e32 v35, vcc, 0, v51, vcc
	global_load_dword v84, v[34:35], off offset:2048
	v_add_co_u32_e32 v34, vcc, s0, v50
	s_mov_b32 s0, 0x10000
	s_nop 0
	v_addc_co_u32_e32 v35, vcc, 0, v51, vcc
	global_load_dword v83, v[50:51], off
	global_load_dword v48, v[34:35], off
	v_add_co_u32_e32 v34, vcc, s0, v50
	s_mov_b32 s0, 0x16000
	s_nop 0
	v_addc_co_u32_e32 v35, vcc, 0, v51, vcc
	global_load_dword v49, v[34:35], off offset:2048
	v_add_co_u32_e32 v34, vcc, s0, v50
	s_mov_b32 s0, 0x1b000
	s_nop 0
	v_addc_co_u32_e32 v35, vcc, 0, v51, vcc
	global_load_dword v81, v[34:35], off
	v_add_co_u32_e32 v34, vcc, s0, v50
	s_mov_b32 s0, 0x21000
	s_nop 0
	v_addc_co_u32_e32 v35, vcc, 0, v51, vcc
	global_load_dword v82, v[34:35], off offset:2048
	v_add_co_u32_e32 v34, vcc, s0, v50
	s_mov_b32 s0, 0x26000
	s_nop 0
	v_addc_co_u32_e32 v35, vcc, 0, v51, vcc
	global_load_dword v46, v[34:35], off
	v_add_co_u32_e32 v34, vcc, s0, v50
	s_mov_b32 s0, 0x2c000
	s_nop 0
	v_addc_co_u32_e32 v35, vcc, 0, v51, vcc
	global_load_dword v47, v[34:35], off offset:2048
	v_add_co_u32_e32 v34, vcc, s0, v50
	s_mov_b32 s0, 0x31000
	s_nop 0
	v_addc_co_u32_e32 v35, vcc, 0, v51, vcc
	global_load_dword v79, v[34:35], off
	v_add_co_u32_e32 v34, vcc, s0, v50
	s_mov_b32 s0, 0x37000
	s_nop 0
	v_addc_co_u32_e32 v35, vcc, 0, v51, vcc
	global_load_dword v80, v[34:35], off offset:2048
	v_add_co_u32_e32 v34, vcc, s0, v50
	s_mov_b32 s0, 0x3c000
	s_nop 0
	v_addc_co_u32_e32 v35, vcc, 0, v51, vcc
	global_load_dword v44, v[34:35], off
	v_add_co_u32_e32 v34, vcc, s0, v50
	s_mov_b32 s0, 0x42000
	s_nop 0
	v_addc_co_u32_e32 v35, vcc, 0, v51, vcc
	global_load_dword v45, v[34:35], off offset:2048
	v_add_co_u32_e32 v34, vcc, s0, v50
	s_mov_b32 s0, 0x47000
	s_nop 0
	v_addc_co_u32_e32 v35, vcc, 0, v51, vcc
	global_load_dword v77, v[34:35], off
	v_add_co_u32_e32 v34, vcc, s0, v50
	s_mov_b32 s0, 0x4d000
	s_nop 0
	v_addc_co_u32_e32 v35, vcc, 0, v51, vcc
	global_load_dword v78, v[34:35], off offset:2048
	v_add_co_u32_e32 v34, vcc, s0, v50
	s_mov_b32 s0, 0x52000
	s_nop 0
	v_addc_co_u32_e32 v35, vcc, 0, v51, vcc
	global_load_dword v42, v[34:35], off
	v_add_co_u32_e32 v34, vcc, s0, v50
	s_mov_b32 s0, 0x58000
	s_nop 0
	v_addc_co_u32_e32 v35, vcc, 0, v51, vcc
	global_load_dword v43, v[34:35], off offset:2048
	v_add_co_u32_e32 v34, vcc, s0, v50
	s_mov_b32 s0, 0x5d000
	s_nop 0
	v_addc_co_u32_e32 v35, vcc, 0, v51, vcc
	global_load_dword v75, v[34:35], off
	v_add_co_u32_e32 v34, vcc, s0, v50
	s_mov_b32 s0, 0x63000
	s_nop 0
	v_addc_co_u32_e32 v35, vcc, 0, v51, vcc
	global_load_dword v76, v[34:35], off offset:2048
	v_add_co_u32_e32 v34, vcc, s0, v50
	s_mov_b32 s0, 0x68000
	s_nop 0
	v_addc_co_u32_e32 v35, vcc, 0, v51, vcc
	global_load_dword v40, v[34:35], off
	v_add_co_u32_e32 v34, vcc, s0, v50
	s_mov_b32 s0, 0x6e000
	s_nop 0
	v_addc_co_u32_e32 v35, vcc, 0, v51, vcc
	global_load_dword v41, v[34:35], off offset:2048
	v_add_co_u32_e32 v34, vcc, s0, v50
	s_mov_b32 s0, 0x73000
	s_nop 0
	v_addc_co_u32_e32 v35, vcc, 0, v51, vcc
	global_load_dword v73, v[34:35], off
	v_add_co_u32_e32 v34, vcc, s0, v50
	s_mov_b32 s0, 0x79000
	s_nop 0
	v_addc_co_u32_e32 v35, vcc, 0, v51, vcc
	global_load_dword v74, v[34:35], off offset:2048
	v_add_co_u32_e32 v34, vcc, s0, v50
	s_mov_b32 s0, 0x7e000
	s_nop 0
	v_addc_co_u32_e32 v35, vcc, 0, v51, vcc
	global_load_dword v38, v[34:35], off
	v_add_co_u32_e32 v34, vcc, s0, v50
	s_mov_b32 s0, 0x84000
	s_nop 0
	v_addc_co_u32_e32 v35, vcc, 0, v51, vcc
	global_load_dword v39, v[34:35], off offset:2048
	v_add_co_u32_e32 v34, vcc, s0, v50
	s_mov_b32 s0, 0x89000
	s_nop 0
	v_addc_co_u32_e32 v35, vcc, 0, v51, vcc
	global_load_dword v71, v[34:35], off
	v_add_co_u32_e32 v34, vcc, s0, v50
	s_mov_b32 s0, 0x8f000
	s_nop 0
	v_addc_co_u32_e32 v35, vcc, 0, v51, vcc
	global_load_dword v72, v[34:35], off offset:2048
	v_add_co_u32_e32 v34, vcc, s0, v50
	s_mov_b32 s0, 0x94000
	s_nop 0
	v_addc_co_u32_e32 v35, vcc, 0, v51, vcc
	global_load_dword v36, v[34:35], off
	v_add_co_u32_e32 v34, vcc, s0, v50
	s_mov_b32 s0, 0x9a000
	s_nop 0
	v_addc_co_u32_e32 v35, vcc, 0, v51, vcc
	global_load_dword v37, v[34:35], off offset:2048
	v_add_co_u32_e32 v34, vcc, s0, v50
	v_readlane_b32 s0, v251, 40
	s_nop 0
	v_addc_co_u32_e32 v35, vcc, 0, v51, vcc
	global_load_dword v69, v[34:35], off
	v_add_co_u32_e32 v34, vcc, 0x9f000, v50
	v_readlane_b32 s1, v251, 41
	s_nop 0
	v_addc_co_u32_e32 v35, vcc, 0, v51, vcc
	global_load_dword v70, v[34:35], off offset:2048
	v_add_co_u32_e32 v34, vcc, 0xa5000, v50
	s_mov_b64 s[50:51], s[54:55]
	s_nop 0
	v_addc_co_u32_e32 v35, vcc, 0, v51, vcc
	v_add_co_u32_e32 v50, vcc, 0xaa000, v50
	global_load_dword v34, v[34:35], off
	s_nop 0
	v_addc_co_u32_e32 v51, vcc, 0, v51, vcc
	global_load_dword v35, v[50:51], off offset:2048
	v_cndmask_b32_e64 v50, 0, 1, s[0:1]
	v_cmp_ne_u32_e64 s[36:37], 1, v50
	s_andn2_b64 vcc, exec, s[0:1]
	s_cbranch_vccnz .LBB0_1175
; __device__ __forceinline__ void transpose_item(const float* W, int N, bf16* WT, int K, int k0, int n0, int drow0, const float* gk, LAS float* scr, int lane) {
;     ...
;     for (int i = 0; i < 32; ++i) { const int kk = 2 * i + (lane >> 5); float v = wv[i]; if (gk) v *= gk[kk]; scr[kk * 33 + (lane & 31)] = v; }
	v_lshlrev_b32_e32 v51, 2, v0
	s_waitcnt vmcnt(32)
	global_load_dword v204, v51, s[30:31]
	global_load_dword v205, v51, s[30:31] offset:8
	global_load_dword v206, v51, s[30:31] offset:16
	global_load_dword v207, v51, s[30:31] offset:24
	global_load_dword v208, v51, s[30:31] offset:32
	global_load_dword v209, v51, s[30:31] offset:40
	global_load_dword v210, v51, s[30:31] offset:48
	global_load_dword v211, v51, s[30:31] offset:56
	global_load_dword v212, v51, s[30:31] offset:64
	global_load_dword v213, v51, s[30:31] offset:72
	global_load_dword v214, v51, s[30:31] offset:80
	global_load_dword v215, v51, s[30:31] offset:88
	global_load_dword v216, v51, s[30:31] offset:96
	global_load_dword v217, v51, s[30:31] offset:104
	global_load_dword v218, v51, s[30:31] offset:112
	global_load_dword v219, v51, s[30:31] offset:120
	global_load_dword v220, v51, s[30:31] offset:128
	global_load_dword v221, v51, s[30:31] offset:136
	global_load_dword v222, v51, s[30:31] offset:144
	global_load_dword v223, v51, s[30:31] offset:152
	global_load_dword v224, v51, s[30:31] offset:160
	global_load_dword v225, v51, s[30:31] offset:168
	global_load_dword v226, v51, s[30:31] offset:176
	global_load_dword v227, v51, s[30:31] offset:184
	global_load_dword v228, v51, s[30:31] offset:192
	global_load_dword v229, v51, s[30:31] offset:200
	global_load_dword v230, v51, s[30:31] offset:208
	global_load_dword v231, v51, s[30:31] offset:216
	global_load_dword v232, v51, s[30:31] offset:224
	global_load_dword v233, v51, s[30:31] offset:232
	global_load_dword v234, v51, s[30:31] offset:240
	s_waitcnt vmcnt(62)
	global_load_dword v235, v51, s[30:31] offset:248
	s_waitcnt vmcnt(0)
	v_mov_b32_e32 v50, v204
	v_mov_b32_e32 v85, v205
	s_waitcnt vmcnt(0)
	v_mul_f32_e32 v50, v83, v50
	v_mul_f32_e32 v85, v84, v85
	ds_write_b32 v3, v50
	v_add_u32_e32 v50, v1, v56
	ds_write_b32 v50, v85
	v_mov_b32_e32 v50, v206
	s_nop 0
	v_mov_b32_e32 v51, v207
	s_waitcnt vmcnt(0)
	v_pk_mul_f32 v[50:51], v[48:49], v[50:51]
	s_cbranch_execnz .LBB0_1117

; __device__ __forceinline__ void transpose_item(const float* W, int N, bf16* WT, int K, int k0, int n0, int drow0, const float* gk, LAS float* scr, int lane) {
;     ...
;     for (int i = 0; i < 32; ++i) wv[i] = W[(size_t)(k0 + 2 * i + (lane >> 5)) * N + n0 + (lane & 31)];
; __device__ __forceinline__ void p0_weight_item(const Args& a, int l, int r, LAS float* scr, int lane) {
;     ...
;         if (r < 2 * IT_BIG) { const int up = r >= IT_BIG; const int it = r - up * IT_BIG; const int kb = it / 88, nb = it % 88, k0 = 64 * kb, n0 = 32 * nb;
;             const float* W = a.in[(f ? 29 : 2) + up] + (size_t)l * DM * FF;
;             transpose_item(W, FF, gu, DM, k0, n0, (n0 >> 7) * 256 + up * 128 + (n0 & 127), nrm + k0, scr, lane); return; }
.LBB0_1143:
	s_andn2_b64 vcc, exec, s[0:1]
	s_cbranch_vccnz .LBB0_1030
	s_cmpk_gt_i32 s39, 0x57f
	s_cselect_b64 s[4:5], -1, 0
	s_and_b64 s[0:1], s[4:5], exec
	v_readlane_b32 s40, v250, 11
	s_cselect_b32 s0, 0xfffffa80, 0
	v_readlane_b32 s44, v250, 15
	v_readlane_b32 s45, v250, 16
	v_readlane_b32 s46, v250, 17
	v_readlane_b32 s47, v250, 18
	s_cselect_b32 s1, s47, s45
	s_cselect_b32 s7, s46, s44
	s_add_i32 s0, s0, s27
	s_addk_i32 s0, 0x2100
	s_mul_hi_i32 s6, s0, 0x2e8ba2e9
	s_lshr_b32 s24, s6, 31
	s_ashr_i32 s6, s6, 4
	s_add_i32 s6, s6, s24
	s_mul_i32 s24, s6, 0x58
	s_sub_i32 s24, s0, s24
	s_lshl_b32 s28, s6, 6
	s_lshl_b32 s6, s24, 5
	s_add_u32 s25, s7, s81
	s_addc_u32 s36, s1, s80
	s_ashr_i32 s29, s28, 31
	s_lshl_b64 s[0:1], s[28:29], 2
	v_readlane_b32 s7, v254, 31
	s_add_u32 s30, s7, s0
	v_readlane_b32 s0, v254, 32
	s_addc_u32 s31, s0, s1
	s_ashr_i32 s7, s6, 31
	s_lshl_b64 s[0:1], s[6:7], 2
	s_add_u32 s0, s25, s0
	s_addc_u32 s1, s36, s1
	v_lshlrev_b32_e32 v144, 2, v2
	v_or_b32_e32 v75, s28, v0
	v_lshl_add_u64 v[50:51], s[0:1], 0, v[144:145]
	v_mad_i64_i32 v[34:35], s[0:1], v75, s85, v[50:51]
	global_load_dword v84, v[34:35], off
	v_or_b32_e32 v34, 2, v75
	v_mad_i64_i32 v[34:35], s[0:1], v34, s85, v[50:51]
	global_load_dword v85, v[34:35], off
	v_or_b32_e32 v34, 4, v75
	v_mad_i64_i32 v[34:35], s[0:1], v34, s85, v[50:51]
	global_load_dword v48, v[34:35], off
	v_or_b32_e32 v34, 6, v75
	v_mad_i64_i32 v[34:35], s[0:1], v34, s85, v[50:51]
	global_load_dword v49, v[34:35], off
	v_or_b32_e32 v34, 8, v75
	v_mad_i64_i32 v[34:35], s[0:1], v34, s85, v[50:51]
	global_load_dword v82, v[34:35], off
	v_or_b32_e32 v34, 10, v75
	v_mad_i64_i32 v[34:35], s[0:1], v34, s85, v[50:51]
	global_load_dword v83, v[34:35], off
	v_or_b32_e32 v34, 12, v75
	v_mad_i64_i32 v[34:35], s[0:1], v34, s85, v[50:51]
	global_load_dword v46, v[34:35], off
	v_or_b32_e32 v34, 14, v75
	v_mad_i64_i32 v[34:35], s[0:1], v34, s85, v[50:51]
	global_load_dword v47, v[34:35], off
	v_or_b32_e32 v34, 16, v75
	v_mad_i64_i32 v[34:35], s[0:1], v34, s85, v[50:51]
	global_load_dword v80, v[34:35], off
	v_or_b32_e32 v34, 18, v75
	v_mad_i64_i32 v[34:35], s[0:1], v34, s85, v[50:51]
	global_load_dword v81, v[34:35], off
	v_or_b32_e32 v34, 20, v75
	v_mad_i64_i32 v[34:35], s[0:1], v34, s85, v[50:51]
	global_load_dword v44, v[34:35], off
	v_or_b32_e32 v34, 22, v75
	v_mad_i64_i32 v[34:35], s[0:1], v34, s85, v[50:51]
	global_load_dword v45, v[34:35], off
	v_or_b32_e32 v34, 24, v75
	v_mad_i64_i32 v[34:35], s[0:1], v34, s85, v[50:51]
	global_load_dword v78, v[34:35], off
	v_or_b32_e32 v34, 26, v75
	v_mad_i64_i32 v[34:35], s[0:1], v34, s85, v[50:51]
	global_load_dword v79, v[34:35], off
	v_or_b32_e32 v34, 28, v75
	v_mad_i64_i32 v[34:35], s[0:1], v34, s85, v[50:51]
	global_load_dword v42, v[34:35], off
	v_or_b32_e32 v34, 30, v75
	v_mad_i64_i32 v[34:35], s[0:1], v34, s85, v[50:51]
	global_load_dword v43, v[34:35], off
	v_or_b32_e32 v34, 32, v75
	v_mad_i64_i32 v[34:35], s[0:1], v34, s85, v[50:51]
	global_load_dword v76, v[34:35], off
	v_or_b32_e32 v34, 34, v75
	v_mad_i64_i32 v[34:35], s[0:1], v34, s85, v[50:51]
	global_load_dword v77, v[34:35], off
	v_or_b32_e32 v34, 36, v75
	v_mad_i64_i32 v[34:35], s[0:1], v34, s85, v[50:51]
	global_load_dword v40, v[34:35], off
	v_or_b32_e32 v34, 38, v75
	v_mad_i64_i32 v[34:35], s[0:1], v34, s85, v[50:51]
	global_load_dword v41, v[34:35], off
	v_or_b32_e32 v34, 40, v75
	v_mad_i64_i32 v[34:35], s[0:1], v34, s85, v[50:51]
	global_load_dword v73, v[34:35], off
	v_or_b32_e32 v34, 42, v75
	v_mad_i64_i32 v[34:35], s[0:1], v34, s85, v[50:51]
	global_load_dword v74, v[34:35], off
	v_or_b32_e32 v34, 44, v75
	v_mad_i64_i32 v[34:35], s[0:1], v34, s85, v[50:51]
	global_load_dword v38, v[34:35], off
	v_or_b32_e32 v34, 46, v75
	v_mad_i64_i32 v[34:35], s[0:1], v34, s85, v[50:51]
	global_load_dword v39, v[34:35], off
	v_or_b32_e32 v34, 48, v75
	v_mad_i64_i32 v[34:35], s[0:1], v34, s85, v[50:51]
	global_load_dword v71, v[34:35], off
	v_or_b32_e32 v34, 50, v75
	v_mad_i64_i32 v[34:35], s[0:1], v34, s85, v[50:51]
	global_load_dword v72, v[34:35], off
	v_or_b32_e32 v34, 52, v75
	v_mad_i64_i32 v[34:35], s[0:1], v34, s85, v[50:51]
	global_load_dword v36, v[34:35], off
	v_or_b32_e32 v34, 54, v75
	v_mad_i64_i32 v[34:35], s[0:1], v34, s85, v[50:51]
	global_load_dword v37, v[34:35], off
	v_or_b32_e32 v34, 56, v75
	v_mad_i64_i32 v[34:35], s[0:1], v34, s85, v[50:51]
	global_load_dword v69, v[34:35], off
	v_or_b32_e32 v34, 58, v75
	v_mad_i64_i32 v[34:35], s[0:1], v34, s85, v[50:51]
	global_load_dword v70, v[34:35], off
	v_or_b32_e32 v34, 60, v75
	v_mad_i64_i32 v[34:35], s[0:1], v34, s85, v[50:51]
	global_load_dword v34, v[34:35], off
	v_or_b32_e32 v35, 62, v75
	v_mad_i64_i32 v[50:51], s[0:1], v35, s85, v[50:51]
	global_load_dword v35, v[50:51], off
	v_cndmask_b32_e64 v50, 0, 1, s[90:91]
	v_cmp_ne_u32_e64 s[36:37], 1, v50
	s_andn2_b64 vcc, exec, s[90:91]
	v_add_u32_e32 v86, v1, v56
	v_lshlrev_b32_e32 v75, 2, v0
	v_readlane_b32 s41, v250, 12
	v_readlane_b32 s42, v250, 13
	v_readlane_b32 s43, v250, 14
	v_readlane_b32 s48, v250, 19
	v_readlane_b32 s49, v250, 20
	v_readlane_b32 s50, v250, 21
	v_readlane_b32 s51, v250, 22
	v_readlane_b32 s52, v250, 23
	v_readlane_b32 s53, v250, 24
	v_readlane_b32 s54, v250, 25
	v_readlane_b32 s55, v250, 26
	s_cbranch_vccnz .LBB0_1167
; __device__ __forceinline__ void transpose_item(const float* W, int N, bf16* WT, int K, int k0, int n0, int drow0, const float* gk, LAS float* scr, int lane) {
;     ...
;     for (int i = 0; i < 32; ++i) { const int kk = 2 * i + (lane >> 5); float v = wv[i]; if (gk) v *= gk[kk]; scr[kk * 33 + (lane & 31)] = v; }
	s_waitcnt vmcnt(32)
	global_load_dword v204, v75, s[30:31]
	global_load_dword v205, v75, s[30:31] offset:8
	global_load_dword v206, v75, s[30:31] offset:16
	global_load_dword v207, v75, s[30:31] offset:24
	global_load_dword v208, v75, s[30:31] offset:32
	global_load_dword v209, v75, s[30:31] offset:40
	global_load_dword v210, v75, s[30:31] offset:48
	global_load_dword v211, v75, s[30:31] offset:56
	global_load_dword v212, v75, s[30:31] offset:64
	global_load_dword v213, v75, s[30:31] offset:72
	global_load_dword v214, v75, s[30:31] offset:80
	global_load_dword v215, v75, s[30:31] offset:88
	global_load_dword v216, v75, s[30:31] offset:96
	global_load_dword v217, v75, s[30:31] offset:104
	global_load_dword v218, v75, s[30:31] offset:112
	global_load_dword v219, v75, s[30:31] offset:120
	global_load_dword v220, v75, s[30:31] offset:128
	global_load_dword v221, v75, s[30:31] offset:136
	global_load_dword v222, v75, s[30:31] offset:144
	global_load_dword v223, v75, s[30:31] offset:152
	global_load_dword v224, v75, s[30:31] offset:160
	global_load_dword v225, v75, s[30:31] offset:168
	global_load_dword v226, v75, s[30:31] offset:176
	global_load_dword v227, v75, s[30:31] offset:184
	global_load_dword v228, v75, s[30:31] offset:192
	global_load_dword v229, v75, s[30:31] offset:200
	global_load_dword v230, v75, s[30:31] offset:208
	global_load_dword v231, v75, s[30:31] offset:216
	global_load_dword v232, v75, s[30:31] offset:224
	global_load_dword v233, v75, s[30:31] offset:232
	global_load_dword v234, v75, s[30:31] offset:240
	s_waitcnt vmcnt(62)
	global_load_dword v235, v75, s[30:31] offset:248
	s_waitcnt vmcnt(0)
	v_mov_b32_e32 v50, v204
	v_mov_b32_e32 v51, v205
	s_waitcnt vmcnt(0)
	v_mul_f32_e32 v50, v84, v50
	v_mul_f32_e32 v51, v85, v51
	ds_write_b32 v3, v50
	ds_write_b32 v86, v51
	v_mov_b32_e32 v50, v206
	v_mov_b32_e32 v51, v207
	s_waitcnt vmcnt(0)
	v_pk_mul_f32 v[50:51], v[48:49], v[50:51]
	s_cbranch_execnz .LBB0_1147

; __device__ __forceinline__ void transpose_item(const float* W, int N, bf16* WT, int K, int k0, int n0, int drow0, const float* gk, LAS float* scr, int lane) {
;     ...
;     for (int i = 0; i < 32; ++i) { const int kk = 2 * i + (lane >> 5); float v = wv[i]; if (gk) v *= gk[kk]; scr[kk * 33 + (lane & 31)] = v; }
.LBB0_1147:
	s_waitcnt vmcnt(0)
	v_add_u32_e32 v48, v1, v57
	ds_write2_b32 v48, v50, v51 offset1:66
	s_and_b64 vcc, exec, s[36:37]
	v_add_u32_e32 v50, v1, v58
	s_cbranch_vccnz .LBB0_1168
	v_mov_b32_e32 v48, v208
	v_mov_b32_e32 v49, v209
	s_waitcnt vmcnt(1)
	v_mul_f32_e32 v48, v82, v48
	s_waitcnt vmcnt(0)
	v_mul_f32_e32 v49, v83, v49
	ds_write2_b32 v50, v48, v49 offset1:66
	v_mov_b32_e32 v48, v210
	v_mov_b32_e32 v49, v211
	s_waitcnt vmcnt(0)
	v_pk_mul_f32 v[48:49], v[46:47], v[48:49]
	s_cbranch_execnz .LBB0_1150

; __device__ __forceinline__ void transpose_item(const float* W, int N, bf16* WT, int K, int k0, int n0, int drow0, const float* gk, LAS float* scr, int lane) {
;     ...
;     for (int i = 0; i < 32; ++i) { const int kk = 2 * i + (lane >> 5); float v = wv[i]; if (gk) v *= gk[kk]; scr[kk * 33 + (lane & 31)] = v; }
.LBB0_1150:
	v_add_u32_e32 v46, v1, v59
	ds_write2_b32 v46, v48, v49 offset1:66
	s_and_b64 vcc, exec, s[36:37]
	v_add_u32_e32 v48, v1, v60
	s_cbranch_vccnz .LBB0_1169
	v_mov_b32_e32 v46, v212
	v_mov_b32_e32 v47, v213
	s_waitcnt vmcnt(1)
	v_mul_f32_e32 v46, v80, v46
	s_waitcnt vmcnt(0)
	v_mul_f32_e32 v47, v81, v47
	ds_write2_b32 v48, v46, v47 offset1:66
	v_mov_b32_e32 v46, v214
	v_mov_b32_e32 v47, v215
	s_waitcnt vmcnt(0)
	v_pk_mul_f32 v[46:47], v[44:45], v[46:47]
	s_cbranch_execnz .LBB0_1153

; __device__ __forceinline__ void transpose_item(const float* W, int N, bf16* WT, int K, int k0, int n0, int drow0, const float* gk, LAS float* scr, int lane) {
;     ...
;     for (int i = 0; i < 32; ++i) { const int kk = 2 * i + (lane >> 5); float v = wv[i]; if (gk) v *= gk[kk]; scr[kk * 33 + (lane & 31)] = v; }
.LBB0_1153:
	v_add_u32_e32 v44, v1, v61
	ds_write2_b32 v44, v46, v47 offset1:66
	s_and_b64 vcc, exec, s[36:37]
	v_add_u32_e32 v46, v1, v62
	s_cbranch_vccnz .LBB0_1170
	v_mov_b32_e32 v44, v216
	v_mov_b32_e32 v45, v217
	s_waitcnt vmcnt(1)
	v_mul_f32_e32 v44, v78, v44
	s_waitcnt vmcnt(0)
	v_mul_f32_e32 v45, v79, v45
	ds_write2_b32 v46, v44, v45 offset1:66
	v_mov_b32_e32 v44, v218
	v_mov_b32_e32 v45, v219
	s_waitcnt vmcnt(0)
	v_pk_mul_f32 v[44:45], v[42:43], v[44:45]
	s_cbranch_execnz .LBB0_1156

; __device__ __forceinline__ void transpose_item(const float* W, int N, bf16* WT, int K, int k0, int n0, int drow0, const float* gk, LAS float* scr, int lane) {
;     ...
;     for (int i = 0; i < 32; ++i) { const int kk = 2 * i + (lane >> 5); float v = wv[i]; if (gk) v *= gk[kk]; scr[kk * 33 + (lane & 31)] = v; }
.LBB0_1156:
	v_add_u32_e32 v42, v1, v63
	ds_write2_b32 v42, v44, v45 offset1:66
	s_and_b64 vcc, exec, s[36:37]
	v_add_u32_e32 v44, v1, v64
	s_cbranch_vccnz .LBB0_1171
	v_mov_b32_e32 v42, v220
	v_mov_b32_e32 v43, v221
	s_waitcnt vmcnt(1)
	v_mul_f32_e32 v42, v76, v42
	s_waitcnt vmcnt(0)
	v_mul_f32_e32 v43, v77, v43
	ds_write2_b32 v44, v42, v43 offset1:66
	v_mov_b32_e32 v42, v222
	v_mov_b32_e32 v43, v223
	s_waitcnt vmcnt(0)
	v_pk_mul_f32 v[42:43], v[40:41], v[42:43]
	s_cbranch_execnz .LBB0_1159

; __device__ __forceinline__ void transpose_item(const float* W, int N, bf16* WT, int K, int k0, int n0, int drow0, const float* gk, LAS float* scr, int lane) {
;     ...
;     for (int i = 0; i < 32; ++i) { const int kk = 2 * i + (lane >> 5); float v = wv[i]; if (gk) v *= gk[kk]; scr[kk * 33 + (lane & 31)] = v; }
.LBB0_1159:
	v_add_u32_e32 v40, v1, v65
	ds_write2_b32 v40, v42, v43 offset1:66
	s_and_b64 vcc, exec, s[36:37]
	v_add_u32_e32 v42, v1, v66
	s_cbranch_vccnz .LBB0_1172
	v_mov_b32_e32 v40, v224
	v_mov_b32_e32 v41, v225
	s_waitcnt vmcnt(1)
	v_mul_f32_e32 v40, v73, v40
	s_waitcnt vmcnt(0)
	v_mul_f32_e32 v41, v74, v41
	ds_write2_b32 v42, v40, v41 offset1:66
	v_mov_b32_e32 v40, v226
	v_mov_b32_e32 v41, v227
	s_waitcnt vmcnt(0)
	v_pk_mul_f32 v[40:41], v[38:39], v[40:41]
	s_cbranch_execnz .LBB0_1162

; __device__ __forceinline__ void transpose_item(const float* W, int N, bf16* WT, int K, int k0, int n0, int drow0, const float* gk, LAS float* scr, int lane) {
;     ...
;     for (int i = 0; i < 32; ++i) { const int kk = 2 * i + (lane >> 5); float v = wv[i]; if (gk) v *= gk[kk]; scr[kk * 33 + (lane & 31)] = v; }
.LBB0_1162:
	v_add_u32_e32 v38, v1, v67
	ds_write2_b32 v38, v40, v41 offset1:66
	s_and_b64 vcc, exec, s[36:37]
	v_add_u32_e32 v40, v1, v68
	s_cbranch_vccnz .LBB0_1173
	v_mov_b32_e32 v38, v228
	v_mov_b32_e32 v39, v229
	s_waitcnt vmcnt(1)
	v_mul_f32_e32 v38, v71, v38
	s_waitcnt vmcnt(0)
	v_mul_f32_e32 v39, v72, v39
	ds_write2_b32 v40, v38, v39 offset1:66
	v_mov_b32_e32 v38, v230
	v_mov_b32_e32 v39, v231
	s_waitcnt vmcnt(0)
	v_pk_mul_f32 v[38:39], v[36:37], v[38:39]
	s_cbranch_execnz .LBB0_1165

; __device__ __forceinline__ void transpose_item(const float* W, int N, bf16* WT, int K, int k0, int n0, int drow0, const float* gk, LAS float* scr, int lane) {
;     ...
;     for (int i = 0; i < 32; ++i) { const int kk = 2 * i + (lane >> 5); float v = wv[i]; if (gk) v *= gk[kk]; scr[kk * 33 + (lane & 31)] = v; }
.LBB0_1165:
	ds_write2_b32 v40, v38, v39 offset0:132 offset1:198
	s_and_b64 vcc, exec, s[36:37]
	v_add_u32_e32 v38, 0x400, v40
	s_cbranch_vccnz .LBB0_1174
	v_mov_b32_e32 v36, v232
	v_mov_b32_e32 v37, v233
	s_waitcnt vmcnt(1)
	v_mul_f32_e32 v36, v69, v36
	s_waitcnt vmcnt(0)
	v_mul_f32_e32 v37, v70, v37
	ds_write2_b32 v38, v36, v37 offset0:8 offset1:74
	v_mov_b32_e32 v36, v234
	v_mov_b32_e32 v37, v235
	s_waitcnt vmcnt(0)
	v_pk_mul_f32 v[36:37], v[34:35], v[36:37]
	s_cbranch_execnz .LBB0_1029
	s_branch .LBB0_1028

; __device__ __forceinline__ unsigned pk2(float lo, float hi) { return pg8::cvt_pk_bf16(lo, hi); }
; __device__ __forceinline__ void ret_out(const Args& a, int tile, LAS unsigned char* lds, int tid, int lane, int wave) {
;     ...
; #pragma unroll 1
;     for (int h = 0; h < 4; ++h)
; #pragma unroll
;         for (int et = 0; et < 4; ++et) { u32x2* yp = (u32x2*)(Y + (size_t)(t0 + cb * 16 + fr) * DM + 256 + h * 128 + hv * 64 + et * 16 + 4 * fq); const u32x2 r = *yp;
;             u32x2 w; w.x = pk2(__uint_as_float(r.x << 16) * rstd, __uint_as_float(r.x & 0xffff0000u) * rstd); w.y = pk2(__uint_as_float(r.y << 16) * rstd, __uint_as_float(r.y & 0xffff0000u) * rstd);
;             *yp = w; }
.LBB0_1471:
	global_load_dwordx2 v[68:69], v[0:1], off offset:-64
	global_load_dwordx2 v[70:71], v[0:1], off offset:-32
	global_load_dwordx2 v[72:73], v[0:1], off
	global_load_dwordx2 v[74:75], v[0:1], off offset:32
	global_load_dwordx2 v[76:77], v[0:1], off offset:192
	global_load_dwordx2 v[78:79], v[0:1], off offset:224
	global_load_dwordx2 v[80:81], v[0:1], off offset:256
	global_load_dwordx2 v[82:83], v[0:1], off offset:288
	global_load_dwordx2 v[84:85], v[0:1], off offset:448
	global_load_dwordx2 v[86:87], v[0:1], off offset:480
	global_load_dwordx2 v[88:89], v[0:1], off offset:512
	global_load_dwordx2 v[98:99], v[0:1], off offset:544
	global_load_dwordx2 v[100:101], v[0:1], off offset:704
	global_load_dwordx2 v[102:103], v[0:1], off offset:736
	global_load_dwordx2 v[104:105], v[0:1], off offset:768
	global_load_dwordx2 v[6:7], v[0:1], off offset:800
	s_waitcnt vmcnt(15)
	v_lshlrev_b32_e32 v3, 16, v68
	v_and_b32_e32 v68, 0xffff0000, v68
	v_lshlrev_b32_e32 v4, 16, v69
	v_and_b32_e32 v69, 0xffff0000, v69
	v_mul_f32_e32 v3, v2, v3
	v_mul_f32_e32 v68, v2, v68
	v_mul_f32_e32 v4, v2, v4
	v_mul_f32_e32 v69, v2, v69
	v_cvt_pk_bf16_f32 v68, v3, v68
	v_cvt_pk_bf16_f32 v69, v4, v69
	global_store_dwordx2 v[0:1], v[68:69], off offset:-64
	s_waitcnt vmcnt(15)
	v_lshlrev_b32_e32 v3, 16, v70
	v_and_b32_e32 v70, 0xffff0000, v70
	v_lshlrev_b32_e32 v4, 16, v71
	v_and_b32_e32 v71, 0xffff0000, v71
	v_mul_f32_e32 v3, v2, v3
	v_mul_f32_e32 v70, v2, v70
	v_mul_f32_e32 v4, v2, v4
	v_mul_f32_e32 v71, v2, v71
	v_cvt_pk_bf16_f32 v70, v3, v70
	v_cvt_pk_bf16_f32 v71, v4, v71
	global_store_dwordx2 v[0:1], v[70:71], off offset:-32
	s_waitcnt vmcnt(15)
	v_lshlrev_b32_e32 v3, 16, v72
	v_and_b32_e32 v72, 0xffff0000, v72
	v_lshlrev_b32_e32 v4, 16, v73
	v_and_b32_e32 v73, 0xffff0000, v73
	v_mul_f32_e32 v3, v2, v3
	v_mul_f32_e32 v72, v2, v72
	v_mul_f32_e32 v4, v2, v4
	v_mul_f32_e32 v73, v2, v73
	v_cvt_pk_bf16_f32 v72, v3, v72
	v_cvt_pk_bf16_f32 v73, v4, v73
	global_store_dwordx2 v[0:1], v[72:73], off
	s_waitcnt vmcnt(15)
	v_lshlrev_b32_e32 v3, 16, v74
	v_and_b32_e32 v74, 0xffff0000, v74
	v_lshlrev_b32_e32 v4, 16, v75
	v_and_b32_e32 v75, 0xffff0000, v75
	v_mul_f32_e32 v3, v2, v3
	v_mul_f32_e32 v74, v2, v74
	v_mul_f32_e32 v4, v2, v4
	v_mul_f32_e32 v75, v2, v75
	v_cvt_pk_bf16_f32 v74, v3, v74
	v_cvt_pk_bf16_f32 v75, v4, v75
	global_store_dwordx2 v[0:1], v[74:75], off offset:32
	s_waitcnt vmcnt(15)
	v_lshlrev_b32_e32 v3, 16, v76
	v_and_b32_e32 v76, 0xffff0000, v76
	v_lshlrev_b32_e32 v4, 16, v77
	v_and_b32_e32 v77, 0xffff0000, v77
	v_mul_f32_e32 v3, v2, v3
	v_mul_f32_e32 v76, v2, v76
	v_mul_f32_e32 v4, v2, v4
	v_mul_f32_e32 v77, v2, v77
	v_cvt_pk_bf16_f32 v76, v3, v76
	v_cvt_pk_bf16_f32 v77, v4, v77
	global_store_dwordx2 v[0:1], v[76:77], off offset:192
	s_waitcnt vmcnt(15)
	v_lshlrev_b32_e32 v3, 16, v78
	v_and_b32_e32 v78, 0xffff0000, v78
	v_lshlrev_b32_e32 v4, 16, v79
	v_and_b32_e32 v79, 0xffff0000, v79
	v_mul_f32_e32 v3, v2, v3
	v_mul_f32_e32 v78, v2, v78
	v_mul_f32_e32 v4, v2, v4
	v_mul_f32_e32 v79, v2, v79
	v_cvt_pk_bf16_f32 v78, v3, v78
	v_cvt_pk_bf16_f32 v79, v4, v79
	global_store_dwordx2 v[0:1], v[78:79], off offset:224
	s_waitcnt vmcnt(15)
	v_lshlrev_b32_e32 v3, 16, v80
	v_and_b32_e32 v80, 0xffff0000, v80
	v_lshlrev_b32_e32 v4, 16, v81
	v_and_b32_e32 v81, 0xffff0000, v81
	v_mul_f32_e32 v3, v2, v3
	v_mul_f32_e32 v80, v2, v80
	v_mul_f32_e32 v4, v2, v4
	v_mul_f32_e32 v81, v2, v81
	v_cvt_pk_bf16_f32 v80, v3, v80
	v_cvt_pk_bf16_f32 v81, v4, v81
	global_store_dwordx2 v[0:1], v[80:81], off offset:256
	s_waitcnt vmcnt(15)
	v_lshlrev_b32_e32 v3, 16, v82
	v_and_b32_e32 v82, 0xffff0000, v82
	v_lshlrev_b32_e32 v4, 16, v83
	v_and_b32_e32 v83, 0xffff0000, v83
	v_mul_f32_e32 v3, v2, v3
	v_mul_f32_e32 v82, v2, v82
	v_mul_f32_e32 v4, v2, v4
	v_mul_f32_e32 v83, v2, v83
	v_cvt_pk_bf16_f32 v82, v3, v82
	v_cvt_pk_bf16_f32 v83, v4, v83
	global_store_dwordx2 v[0:1], v[82:83], off offset:288
	s_waitcnt vmcnt(15)
	v_lshlrev_b32_e32 v3, 16, v84
	v_and_b32_e32 v84, 0xffff0000, v84
	v_lshlrev_b32_e32 v4, 16, v85
	v_and_b32_e32 v85, 0xffff0000, v85
	v_mul_f32_e32 v3, v2, v3
	v_mul_f32_e32 v84, v2, v84
	v_mul_f32_e32 v4, v2, v4
	v_mul_f32_e32 v85, v2, v85
	v_cvt_pk_bf16_f32 v84, v3, v84
	v_cvt_pk_bf16_f32 v85, v4, v85
	global_store_dwordx2 v[0:1], v[84:85], off offset:448
	s_waitcnt vmcnt(15)
; #define LAS __attribute__((address_space(3)))
; template <bool FULL> __device__ __forceinline__ void s5_group(const Args& a, int l, int tile, int g, LAS unsigned char* lds, int lane, int wave) {
;     const bf16* Z = (const bf16*)(a.ws + WS_HZ);
;     const int t0 = tile * 64, fr = lane & 15, fq = lane >> 4;
;     unsigned char* wl = a.ws + WS_W + (size_t)l * WL_STRIDE;
;     const float* tab = (const float*)(wl + WL_S5T) + (size_t)g * 36 * 64; const bf16* BB = (const bf16*)(wl + WL_BB); const bf16* CM = (const bf16*)(wl + WL_CM);
;     float* E = (float*)(a.ws + WS_S5E);
;     LAS unsigned char* bus = lds + OFF_BUS + wave * BUS_WAVE; LAS unsigned char* sst = lds + OFF_SST + wave * SST_WAVE;
;     const float lbr = tab[lane], lbi = tab[64 + lane];
;     const bf16x8 zero8 = {0, 0, 0, 0, 0, 0, 0, 0};
;     bf16x8 bbf[8];
; #pragma unroll
;     for (int kt = 0; kt < 8; ++kt) { bbf[kt] = zero8; if (fq < 2) bbf[kt] = *(const bf16x8*)(BB + (size_t)(g * 128 + kt * 16 + fr) * 16 + 8 * fq); }
;     float sre = 0.f, sim = 0.f;
;     bf16x8 cm[4]; f32x4 dsk;
;     if (FULL) {
;         sre = E[((size_t)(tile * 16 + g) * 2 + 0) * 64 + lane]; sim = E[((size_t)(tile * 16 + g) * 2 + 1) * 64 + lane];
; #pragma unroll
;         for (int ks = 0; ks < 4; ++ks) cm[ks] = *(const bf16x8*)(CM + (size_t)(g * 16 + fr) * 128 + 32 * ks + 8 * fq);
;         dsk = *(const f32x4*)(a.in[14] + (size_t)l * 256 + g * 16 + 4 * fq);
;     }
;     bf16x8 ufa[4]; u32x2 urawa[4];
; #pragma unroll
;     for (int tb = 0; tb < 4; ++tb) { const bf16* zr = Z + (size_t)(t0 + tb * 16 + fr) * IW + g * 16;
;         ufa[tb] = zero8; if (fq < 2) ufa[tb] = *(const bf16x8*)(zr + 8 * fq);
;         if (FULL) urawa[tb] = *(const u32x2*)(zr + 4 * fq); }
; __device__ __forceinline__ void ret_out(const Args& a, int tile, LAS unsigned char* lds, int tid, int lane, int wave) {
;     ...
; #pragma unroll 1
;     for (int h = 0; h < 4; ++h)
; #pragma unroll
;         for (int et = 0; et < 4; ++et) { u32x2* yp = (u32x2*)(Y + (size_t)(t0 + cb * 16 + fr) * DM + 256 + h * 128 + hv * 64 + et * 16 + 4 * fq); const u32x2 r = *yp;
;             u32x2 w; w.x = pk2(__uint_as_float(r.x << 16) * rstd, __uint_as_float(r.x & 0xffff0000u) * rstd); w.y = pk2(__uint_as_float(r.y << 16) * rstd, __uint_as_float(r.y & 0xffff0000u) * rstd);
;             *yp = w; }
	v_lshlrev_b32_e32 v3, 16, v86
	v_and_b32_e32 v86, 0xffff0000, v86
	v_lshlrev_b32_e32 v4, 16, v87
	v_and_b32_e32 v87, 0xffff0000, v87
	v_mul_f32_e32 v3, v2, v3
	v_mul_f32_e32 v86, v2, v86
	v_mul_f32_e32 v4, v2, v4
	v_mul_f32_e32 v87, v2, v87
	v_cvt_pk_bf16_f32 v86, v3, v86
	v_cvt_pk_bf16_f32 v87, v4, v87
	global_store_dwordx2 v[0:1], v[86:87], off offset:480
	s_waitcnt vmcnt(15)
	v_lshlrev_b32_e32 v3, 16, v88
	v_and_b32_e32 v88, 0xffff0000, v88
	v_lshlrev_b32_e32 v4, 16, v89
	v_and_b32_e32 v89, 0xffff0000, v89
	v_mul_f32_e32 v3, v2, v3
	v_mul_f32_e32 v88, v2, v88
	v_mul_f32_e32 v4, v2, v4
	v_mul_f32_e32 v89, v2, v89
	v_cvt_pk_bf16_f32 v88, v3, v88
	v_cvt_pk_bf16_f32 v89, v4, v89
	global_store_dwordx2 v[0:1], v[88:89], off offset:512
	s_waitcnt vmcnt(15)
	v_lshlrev_b32_e32 v3, 16, v98
	v_and_b32_e32 v98, 0xffff0000, v98
	v_lshlrev_b32_e32 v4, 16, v99
	v_and_b32_e32 v99, 0xffff0000, v99
	v_mul_f32_e32 v3, v2, v3
	v_mul_f32_e32 v98, v2, v98
	v_mul_f32_e32 v4, v2, v4
	v_mul_f32_e32 v99, v2, v99
	v_cvt_pk_bf16_f32 v98, v3, v98
	v_cvt_pk_bf16_f32 v99, v4, v99
	global_store_dwordx2 v[0:1], v[98:99], off offset:544
	s_waitcnt vmcnt(15)
	v_lshlrev_b32_e32 v3, 16, v100
	v_and_b32_e32 v100, 0xffff0000, v100
	v_lshlrev_b32_e32 v4, 16, v101
	v_and_b32_e32 v101, 0xffff0000, v101
	v_mul_f32_e32 v3, v2, v3
	v_mul_f32_e32 v100, v2, v100
	v_mul_f32_e32 v4, v2, v4
	v_mul_f32_e32 v101, v2, v101
	v_cvt_pk_bf16_f32 v100, v3, v100
	v_cvt_pk_bf16_f32 v101, v4, v101
	global_store_dwordx2 v[0:1], v[100:101], off offset:704
	s_waitcnt vmcnt(15)
	v_lshlrev_b32_e32 v3, 16, v102
	v_and_b32_e32 v102, 0xffff0000, v102
	v_lshlrev_b32_e32 v4, 16, v103
	v_and_b32_e32 v103, 0xffff0000, v103
	v_mul_f32_e32 v3, v2, v3
	v_mul_f32_e32 v102, v2, v102
	v_mul_f32_e32 v4, v2, v4
	v_mul_f32_e32 v103, v2, v103
	v_cvt_pk_bf16_f32 v102, v3, v102
	v_cvt_pk_bf16_f32 v103, v4, v103
	global_store_dwordx2 v[0:1], v[102:103], off offset:736
	s_waitcnt vmcnt(15)
	v_lshlrev_b32_e32 v3, 16, v104
	v_and_b32_e32 v104, 0xffff0000, v104
	v_lshlrev_b32_e32 v4, 16, v105
	v_and_b32_e32 v105, 0xffff0000, v105
	v_mul_f32_e32 v3, v2, v3
	v_mul_f32_e32 v104, v2, v104
	v_mul_f32_e32 v4, v2, v4
	v_mul_f32_e32 v105, v2, v105
	v_cvt_pk_bf16_f32 v104, v3, v104
	v_cvt_pk_bf16_f32 v105, v4, v105
	global_store_dwordx2 v[0:1], v[104:105], off offset:768
	s_waitcnt vmcnt(15)
	v_lshlrev_b32_e32 v3, 16, v6
	v_and_b32_e32 v6, 0xffff0000, v6
	v_lshlrev_b32_e32 v4, 16, v7
	v_and_b32_e32 v7, 0xffff0000, v7
	v_mul_f32_e32 v3, v2, v3
	v_mul_f32_e32 v6, v2, v6
	v_mul_f32_e32 v4, v2, v4
	v_mul_f32_e32 v7, v2, v7
	v_cvt_pk_bf16_f32 v6, v3, v6
	v_cvt_pk_bf16_f32 v7, v4, v7
	global_store_dwordx2 v[0:1], v[6:7], off offset:800
	s_movk_i32 s0, 0x400
	v_mov_b32_e32 v0, v174
	s_barrier
	v_readlane_b32 s4, v254, 33
	v_readfirstlane_b32 s29, v0
	v_and_b32_e32 v71, 15, v0
	v_bfe_u32 v1, v0, 4, 2
	s_ashr_i32 s28, s29, 6
	v_lshlrev_b32_e32 v70, 3, v1
	v_lshlrev_b32_e32 v68, 2, v1
	v_or_b32_e32 v1, s27, v71
	s_mul_i32 s0, s28, 0x2100
	v_or_b32_e32 v2, 16, v1
	v_and_b32_e32 v69, 63, v0
	s_add_i32 s6, s0, 0
	v_mad_i64_i32 v[72:73], s[0:1], v1, s84, 0
	v_mad_i64_i32 v[74:75], s[0:1], v2, s84, 0
	v_or_b32_e32 v2, 32, v1
	v_or_b32_e32 v1, 48, v1
	v_mad_i64_i32 v[78:79], s[0:1], v1, s84, 0
	v_mul_u32_u24_e32 v1, 0x84, v71
	v_lshlrev_b32_e32 v144, 2, v69
	v_readlane_b32 s5, v254, 34
	v_add_lshl_u32 v5, v68, v1, 2
	v_or_b32_e32 v1, 48, v69
	v_lshl_add_u64 v[80:81], s[4:5], 0, v[144:145]
	v_readlane_b32 s4, v254, 35
	v_and_b32_e32 v0, 48, v0
	v_mul_u32_u24_e32 v101, 0x108, v1
	v_mov_b32_e32 v1, v145
	v_readlane_b32 s5, v254, 36
	v_mad_i64_i32 v[76:77], s[0:1], v2, s84, 0
	s_nop 0
	v_lshl_add_u64 v[82:83], s[4:5], 0, v[0:1]
	v_readlane_b32 s4, v252, 50
	v_readlane_b32 s5, v252, 51
	s_mul_i32 s0, s28, 0x1100
	s_add_i32 s0, s0, 0
	v_lshl_add_u64 v[84:85], s[4:5], 0, v[144:145]
	v_readlane_b32 s4, v254, 53
	v_readlane_b32 s5, v254, 54
	s_add_i32 s1, s0, 0x10800
	v_or_b32_e32 v2, 64, v69
	v_lshl_add_u64 v[86:87], s[4:5], 0, v[0:1]
	v_readlane_b32 s4, v254, 55
	v_mul_u32_u24_e32 v3, 0x110, v71
	v_add_u32_e32 v4, s1, v0
	v_lshlrev_b32_e32 v6, 2, v2
	v_lshlrev_b32_e32 v2, 1, v2
	v_readlane_b32 s5, v254, 56
	s_lshl_b32 s30, s28, 1
	v_cmp_gt_u32_e64 s[38:39], 32, v69
	s_lshl_b32 s31, s36, 4
	v_add_u32_e32 v98, s6, v144
	v_lshl_add_u32 v99, v69, 1, s1
	v_mul_u32_u24_e32 v100, 0x108, v71
	v_lshl_add_u64 v[88:89], s[4:5], 0, v[0:1]
	s_mov_b32 s0, 0
	s_mov_b64 s[4:5], -1
	v_add_u32_e32 v102, s6, v5
	v_add_u32_e32 v103, s6, v6
	v_add_u32_e32 v104, s1, v2
	v_add_u32_e32 v105, v4, v3
	s_branch .LBB0_1474

; __device__ __forceinline__ void transpose_item(const float* W, int N, bf16* WT, int K, int k0, int n0, int drow0, const float* gk, LAS float* scr, int lane) {
;     ...
;     for (int i = 0; i < 32; ++i) wv[i] = W[(size_t)(k0 + 2 * i + (lane >> 5)) * N + n0 + (lane & 31)];
; __device__ __forceinline__ void p0_weight_item(const Args& a, int l, int r, LAS float* scr, int lane) {
;     ...
;     if (r < IT_OUT) {
;         const int kb = r / 32, nb = r % 32, k0 = 64 * kb;
;         const float* gk = (k0 < 256) ? a.in[17] + (size_t)l * 256 + k0 : (k0 < 768 ? a.in[18] + (size_t)l * 512 + (k0 - 256) : a.in[26] + (size_t)l * 256 + (k0 - 768));
;         transpose_item(a.in[27] + (size_t)l * DM * DM, DM, (bf16*)(wl + WL_WOUT), DM, k0, 32 * nb, 32 * nb, gk, scr, lane); return; }
.LBB0_1686:
	s_add_i32 s0, s35, 0xfffb6000
	s_and_b32 s28, s0, 0x3e0
	v_or_b32_e32 v144, s4, v0
	s_lshl_b32 s82, s28, 2
	v_lshl_add_u64 v[50:51], v[18:19], 0, s[82:83]
	v_lshlrev_b64 v[34:35], 12, v[144:145]
	v_lshl_add_u64 v[34:35], v[50:51], 0, v[34:35]
	global_load_dword v83, v[34:35], off
	v_or_b32_e32 v34, 2, v144
	v_mov_b32_e32 v35, v145
	v_lshlrev_b64 v[34:35], 12, v[34:35]
	v_lshl_add_u64 v[34:35], v[50:51], 0, v[34:35]
	global_load_dword v84, v[34:35], off
	v_or_b32_e32 v34, 4, v144
	v_mov_b32_e32 v35, v145
	v_lshlrev_b64 v[34:35], 12, v[34:35]
	v_lshl_add_u64 v[34:35], v[50:51], 0, v[34:35]
	global_load_dword v48, v[34:35], off
	v_or_b32_e32 v34, 6, v144
	v_mov_b32_e32 v35, v145
	v_lshlrev_b64 v[34:35], 12, v[34:35]
	v_lshl_add_u64 v[34:35], v[50:51], 0, v[34:35]
	global_load_dword v49, v[34:35], off
	v_or_b32_e32 v34, 8, v144
	v_mov_b32_e32 v35, v145
	v_lshlrev_b64 v[34:35], 12, v[34:35]
	v_lshl_add_u64 v[34:35], v[50:51], 0, v[34:35]
	global_load_dword v81, v[34:35], off
	v_or_b32_e32 v34, 10, v144
	v_mov_b32_e32 v35, v145
	v_lshlrev_b64 v[34:35], 12, v[34:35]
	v_lshl_add_u64 v[34:35], v[50:51], 0, v[34:35]
	global_load_dword v82, v[34:35], off
	v_or_b32_e32 v34, 12, v144
	v_mov_b32_e32 v35, v145
	v_lshlrev_b64 v[34:35], 12, v[34:35]
	v_lshl_add_u64 v[34:35], v[50:51], 0, v[34:35]
	global_load_dword v46, v[34:35], off
	v_or_b32_e32 v34, 14, v144
	v_mov_b32_e32 v35, v145
	v_lshlrev_b64 v[34:35], 12, v[34:35]
	v_lshl_add_u64 v[34:35], v[50:51], 0, v[34:35]
	global_load_dword v47, v[34:35], off
	v_or_b32_e32 v34, 16, v144
	v_mov_b32_e32 v35, v145
	v_lshlrev_b64 v[34:35], 12, v[34:35]
	v_lshl_add_u64 v[34:35], v[50:51], 0, v[34:35]
	global_load_dword v79, v[34:35], off
	v_or_b32_e32 v34, 18, v144
	v_mov_b32_e32 v35, v145
	v_lshlrev_b64 v[34:35], 12, v[34:35]
	v_lshl_add_u64 v[34:35], v[50:51], 0, v[34:35]
	global_load_dword v80, v[34:35], off
	v_or_b32_e32 v34, 20, v144
	v_mov_b32_e32 v35, v145
	v_lshlrev_b64 v[34:35], 12, v[34:35]
	v_lshl_add_u64 v[34:35], v[50:51], 0, v[34:35]
	global_load_dword v44, v[34:35], off
	v_or_b32_e32 v34, 22, v144
	v_mov_b32_e32 v35, v145
	v_lshlrev_b64 v[34:35], 12, v[34:35]
	v_lshl_add_u64 v[34:35], v[50:51], 0, v[34:35]
	global_load_dword v45, v[34:35], off
	v_or_b32_e32 v34, 24, v144
	v_mov_b32_e32 v35, v145
	v_lshlrev_b64 v[34:35], 12, v[34:35]
	v_lshl_add_u64 v[34:35], v[50:51], 0, v[34:35]
	global_load_dword v77, v[34:35], off
	v_or_b32_e32 v34, 26, v144
	v_mov_b32_e32 v35, v145
	v_lshlrev_b64 v[34:35], 12, v[34:35]
	v_lshl_add_u64 v[34:35], v[50:51], 0, v[34:35]
	global_load_dword v78, v[34:35], off
	v_or_b32_e32 v34, 28, v144
	v_mov_b32_e32 v35, v145
	v_lshlrev_b64 v[34:35], 12, v[34:35]
	v_lshl_add_u64 v[34:35], v[50:51], 0, v[34:35]
	global_load_dword v42, v[34:35], off
	v_or_b32_e32 v34, 30, v144
	v_mov_b32_e32 v35, v145
	v_lshlrev_b64 v[34:35], 12, v[34:35]
	v_lshl_add_u64 v[34:35], v[50:51], 0, v[34:35]
	global_load_dword v43, v[34:35], off
	v_or_b32_e32 v34, 32, v144
	v_mov_b32_e32 v35, v145
	v_lshlrev_b64 v[34:35], 12, v[34:35]
	v_lshl_add_u64 v[34:35], v[50:51], 0, v[34:35]
	global_load_dword v75, v[34:35], off
	v_or_b32_e32 v34, 34, v144
	v_mov_b32_e32 v35, v145
	v_lshlrev_b64 v[34:35], 12, v[34:35]
	v_lshl_add_u64 v[34:35], v[50:51], 0, v[34:35]
	global_load_dword v76, v[34:35], off
	v_or_b32_e32 v34, 36, v144
	v_mov_b32_e32 v35, v145
	v_lshlrev_b64 v[34:35], 12, v[34:35]
	v_lshl_add_u64 v[34:35], v[50:51], 0, v[34:35]
	global_load_dword v40, v[34:35], off
	v_or_b32_e32 v34, 38, v144
	v_mov_b32_e32 v35, v145
	v_lshlrev_b64 v[34:35], 12, v[34:35]
	v_lshl_add_u64 v[34:35], v[50:51], 0, v[34:35]
	global_load_dword v41, v[34:35], off
	v_or_b32_e32 v34, 40, v144
	v_mov_b32_e32 v35, v145
	v_lshlrev_b64 v[34:35], 12, v[34:35]
	v_lshl_add_u64 v[34:35], v[50:51], 0, v[34:35]
	global_load_dword v73, v[34:35], off
	v_or_b32_e32 v34, 42, v144
	v_mov_b32_e32 v35, v145
	v_lshlrev_b64 v[34:35], 12, v[34:35]
	v_lshl_add_u64 v[34:35], v[50:51], 0, v[34:35]
	global_load_dword v74, v[34:35], off
	v_or_b32_e32 v34, 44, v144
	v_mov_b32_e32 v35, v145
	v_lshlrev_b64 v[34:35], 12, v[34:35]
	v_lshl_add_u64 v[34:35], v[50:51], 0, v[34:35]
	global_load_dword v38, v[34:35], off
	v_or_b32_e32 v34, 46, v144
	v_mov_b32_e32 v35, v145
	v_lshlrev_b64 v[34:35], 12, v[34:35]
	v_lshl_add_u64 v[34:35], v[50:51], 0, v[34:35]
	global_load_dword v39, v[34:35], off
	v_or_b32_e32 v34, 48, v144
	v_mov_b32_e32 v35, v145
	v_lshlrev_b64 v[34:35], 12, v[34:35]
	v_lshl_add_u64 v[34:35], v[50:51], 0, v[34:35]
	global_load_dword v71, v[34:35], off
	v_or_b32_e32 v34, 50, v144
	v_mov_b32_e32 v35, v145
	v_lshlrev_b64 v[34:35], 12, v[34:35]
	v_lshl_add_u64 v[34:35], v[50:51], 0, v[34:35]
	global_load_dword v72, v[34:35], off
	v_or_b32_e32 v34, 52, v144
	v_mov_b32_e32 v35, v145
	v_lshlrev_b64 v[34:35], 12, v[34:35]
	v_lshl_add_u64 v[34:35], v[50:51], 0, v[34:35]
	global_load_dword v36, v[34:35], off
	v_or_b32_e32 v34, 54, v144
	v_mov_b32_e32 v35, v145
	v_lshlrev_b64 v[34:35], 12, v[34:35]
	v_lshl_add_u64 v[34:35], v[50:51], 0, v[34:35]
	global_load_dword v37, v[34:35], off
	v_or_b32_e32 v34, 56, v144
	v_mov_b32_e32 v35, v145
	v_lshlrev_b64 v[34:35], 12, v[34:35]
	v_lshl_add_u64 v[34:35], v[50:51], 0, v[34:35]
	global_load_dword v69, v[34:35], off
	v_or_b32_e32 v34, 58, v144
	v_mov_b32_e32 v35, v145
	v_lshlrev_b64 v[34:35], 12, v[34:35]
	v_lshl_add_u64 v[34:35], v[50:51], 0, v[34:35]
	global_load_dword v70, v[34:35], off
	v_or_b32_e32 v34, 60, v144
	v_mov_b32_e32 v35, v145
	v_or_b32_e32 v144, 62, v144
	v_lshlrev_b64 v[34:35], 12, v[34:35]
	v_lshlrev_b64 v[86:87], 12, v[144:145]
	v_lshl_add_u64 v[34:35], v[50:51], 0, v[34:35]
	v_lshl_add_u64 v[50:51], v[50:51], 0, v[86:87]
	global_load_dword v34, v[34:35], off
	s_cmp_lg_u64 s[6:7], 0
	global_load_dword v35, v[50:51], off
	s_cselect_b64 s[0:1], -1, 0
	s_cmp_eq_u64 s[6:7], 0
	s_cbranch_scc1 .LBB0_1822
; __device__ __forceinline__ void transpose_item(const float* W, int N, bf16* WT, int K, int k0, int n0, int drow0, const float* gk, LAS float* scr, int lane) {
;     ...
;     for (int i = 0; i < 32; ++i) { const int kk = 2 * i + (lane >> 5); float v = wv[i]; if (gk) v *= gk[kk]; scr[kk * 33 + (lane & 31)] = v; }
	v_lshlrev_b32_e32 v51, 2, v0
	s_waitcnt vmcnt(32)
	global_load_dword v204, v51, s[6:7]
	global_load_dword v205, v51, s[6:7] offset:8
	global_load_dword v206, v51, s[6:7] offset:16
	global_load_dword v207, v51, s[6:7] offset:24
	global_load_dword v208, v51, s[6:7] offset:32
	global_load_dword v209, v51, s[6:7] offset:40
	global_load_dword v210, v51, s[6:7] offset:48
	global_load_dword v211, v51, s[6:7] offset:56
	global_load_dword v212, v51, s[6:7] offset:64
	global_load_dword v213, v51, s[6:7] offset:72
	global_load_dword v214, v51, s[6:7] offset:80
	global_load_dword v215, v51, s[6:7] offset:88
	global_load_dword v216, v51, s[6:7] offset:96
	global_load_dword v217, v51, s[6:7] offset:104
	global_load_dword v218, v51, s[6:7] offset:112
	global_load_dword v219, v51, s[6:7] offset:120
	global_load_dword v220, v51, s[6:7] offset:128
	global_load_dword v221, v51, s[6:7] offset:136
	global_load_dword v222, v51, s[6:7] offset:144
	global_load_dword v223, v51, s[6:7] offset:152
	global_load_dword v224, v51, s[6:7] offset:160
	global_load_dword v225, v51, s[6:7] offset:168
	global_load_dword v226, v51, s[6:7] offset:176
	global_load_dword v227, v51, s[6:7] offset:184
	global_load_dword v228, v51, s[6:7] offset:192
	global_load_dword v229, v51, s[6:7] offset:200
	global_load_dword v230, v51, s[6:7] offset:208
	global_load_dword v231, v51, s[6:7] offset:216
	global_load_dword v232, v51, s[6:7] offset:224
	global_load_dword v233, v51, s[6:7] offset:232
	global_load_dword v234, v51, s[6:7] offset:240
	s_waitcnt vmcnt(62)
	global_load_dword v235, v51, s[6:7] offset:248
	s_waitcnt vmcnt(0)
	v_mov_b32_e32 v50, v204
	v_mov_b32_e32 v85, v205
	s_waitcnt vmcnt(0)
	v_mul_f32_e32 v50, v83, v50
	v_mul_f32_e32 v85, v84, v85
	ds_write_b32 v3, v50
	v_add_u32_e32 v50, v1, v56
	ds_write_b32 v50, v85
	v_mov_b32_e32 v50, v206
	s_nop 0
	v_mov_b32_e32 v51, v207
	s_waitcnt vmcnt(0)
	v_pk_mul_f32 v[50:51], v[48:49], v[50:51]
	s_cbranch_execnz .LBB0_1689
